# GEMM K-loops: s_setprio 1 raised before the pre-MFMA barrier and s_setprio 0 lowered after the post-MFMA barrier (two fewer issue slots on each MFMA hand-off)
# baseline (speedup 1.0000x reference)
; #define PG8_STAGE(bufoff, gbase, voff) do { _Pragma("unroll") for (int _i = 0; _i < 2; ++_i) \
;         __builtin_amdgcn_global_load_lds((const unsigned*)((const char*)(gbase) + (voff)[_i]), (PG8_LAS unsigned*)(lds + (bufoff) + ldsw + _i * 8192), 16, 0, 0); } while (0)
; #define PG8_LDA(dst, b, h) do { _Pragma("unroll") for (int m = 0; m < 4; ++m) _Pragma("unroll") for (int k = 0; k < 2; ++k) dst[m][k] = *(const PG8_LAS bf16x8*)(lds + PG8_SA(b, h) + aoff + m * 2048 + k * 1024); } while (0)
; #define PG8_LDB(dst, b, h) do { _Pragma("unroll") for (int n = 0; n < 2; ++n) _Pragma("unroll") for (int k = 0; k < 2; ++k) dst[n][k] = *(const PG8_LAS bf16x8*)(lds + PG8_SB(b, h) + boff + n * 2048 + k * 1024); } while (0)
; #define PG8_MMA(ai, bj, At, Bt) do { __builtin_amdgcn_s_setprio(1); _Pragma("unroll") for (int m = 0; m < 4; ++m) _Pragma("unroll") for (int n = 0; n < 2; ++n) _Pragma("unroll") for (int k = 0; k < 2; ++k) \
;         acc[ai][bj][m][n] = __builtin_amdgcn_mfma_f32_16x16x32_bf16(Bt[n][k], At[m][k], acc[ai][bj][m][n], 0, 0, 0); __builtin_amdgcn_s_setprio(0); } while (0)
; #define PG8_WAIT_V(n) asm volatile("s_waitcnt vmcnt(" #n ")" ::: "memory")
; #define PG8_WAIT_L(n) asm volatile("s_waitcnt lgkmcnt(" #n ")" ::: "memory")
; #define PG8_BAR __builtin_amdgcn_s_barrier()
; #define PG8_SCHED __builtin_amdgcn_sched_barrier(0)
; template <class Epi, class Sched, bool ALIGN_EPI = false, bool SP2 = false>
; __device__ __forceinline__ void gemm_phase(PG8_LAS unsigned char* lds, const Gemm g, const Sched& S, const Epi& E) {
;     ...
;             const bool last = (t == nt - 2);
;             const char* a1 = cA + (size_t)(t + 1) * kstep;
;             const char* a2 = last ? nA : cA + (size_t)(t + 2) * kstep; const char* b2 = last ? nB : cB + (size_t)(t + 2) * kstep;
;             const char* a3 = a2 + kstep; const char* b3 = b2 + kstep;
;             if (last && has_next) S.a_ready(nxt);
;             if constexpr (SP2) {
;             PG8_LDB(B0, 0, 0); PG8_LDB(B1, 0, 1); PG8_SCHED; PG8_LDA(At, 0, 0); PG8_STAGE(PG8_SA(1, 1), a1 + hstep, voffA);
;             PG8_WAIT_V(8); PG8_WAIT_L(0); PG8_BAR; PG8_MMA(0, 0, At, B0); PG8_MMA(0, 1, At, B1); PG8_BAR; PG8_SCHED;
;             PG8_LDA(At, 0, 1); PG8_STAGE(PG8_SB(0, 0), b2, voffB); PG8_STAGE(PG8_SB(0, 1), b2 + hstep, voffB); PG8_STAGE(PG8_SA(0, 0), a2, voffA);
.LBB0_111:
	s_add_u32 s76, s12, 0xfffc0080
	s_addc_u32 s77, s13, -1
	s_add_i32 s80, 0, 0x10000
	s_cmp_eq_u32 s69, 12
	s_cselect_b32 s79, s11, s77
	s_cselect_b32 s78, s22, s76
	s_cselect_b32 s77, s23, s67
	s_cselect_b32 s76, s40, s41
	s_add_i32 s86, 0, 0x14000
	v_add_u32_e32 v146, s80, v159
	v_add_u32_e32 v182, s86, v159
	ds_read_b128 v[134:137], v146
	ds_read_b128 v[138:141], v146 offset:1024
	ds_read_b128 v[142:145], v146 offset:2048
	ds_read_b128 v[146:149], v146 offset:3072
	ds_read_b128 v[166:169], v182
	ds_read_b128 v[170:173], v182 offset:1024
	ds_read_b128 v[174:177], v182 offset:2048
	ds_read_b128 v[182:185], v182 offset:3072
	v_lshl_add_u64 v[186:187], s[12:13], 0, v[164:165]
	s_add_i32 m0, s37, 0xc000
	ds_read_b128 v[200:203], v180
	ds_read_b128 v[204:207], v180 offset:1024
	ds_read_b128 v[208:211], v180 offset:2048
	ds_read_b128 v[212:215], v180 offset:3072
	ds_read_b128 v[216:219], v180 offset:4096
	ds_read_b128 v[220:223], v180 offset:5120
	ds_read_b128 v[224:227], v180 offset:6144
	ds_read_b128 v[228:231], v180 offset:7168
	global_load_lds_dwordx4 v[186:187], off
	v_lshl_add_u64 v[186:187], s[12:13], 0, v[162:163]
	s_add_i32 m0, s37, 0xe000
	s_nop 0
	global_load_lds_dwordx4 v[186:187], off
	s_waitcnt vmcnt(8)
	s_waitcnt lgkmcnt(0)
	s_setprio 1
	s_barrier
	v_mfma_f32_16x16x32_bf16 v[130:133], v[134:137], v[200:203], v[130:133]
	v_mfma_f32_16x16x32_bf16 v[126:129], v[142:145], v[200:203], v[126:129]
	v_mfma_f32_16x16x32_bf16 v[114:117], v[134:137], v[208:211], v[114:117]
	v_mfma_f32_16x16x32_bf16 v[110:113], v[142:145], v[208:211], v[110:113]
	v_mfma_f32_16x16x32_bf16 v[98:101], v[134:137], v[216:219], v[98:101]
	v_mfma_f32_16x16x32_bf16 v[94:97], v[142:145], v[216:219], v[94:97]
	v_mfma_f32_16x16x32_bf16 v[78:81], v[134:137], v[224:227], v[78:81]
	v_mfma_f32_16x16x32_bf16 v[74:77], v[142:145], v[224:227], v[74:77]
	v_mfma_f32_16x16x32_bf16 v[130:133], v[138:141], v[204:207], v[130:133]
	v_mfma_f32_16x16x32_bf16 v[126:129], v[146:149], v[204:207], v[126:129]
	v_mfma_f32_16x16x32_bf16 v[114:117], v[138:141], v[212:215], v[114:117]
	v_mfma_f32_16x16x32_bf16 v[110:113], v[146:149], v[212:215], v[110:113]
	v_mfma_f32_16x16x32_bf16 v[98:101], v[138:141], v[220:223], v[98:101]
	v_mfma_f32_16x16x32_bf16 v[94:97], v[146:149], v[220:223], v[94:97]
	v_mfma_f32_16x16x32_bf16 v[78:81], v[138:141], v[228:231], v[78:81]
	v_mfma_f32_16x16x32_bf16 v[74:77], v[146:149], v[228:231], v[74:77]
	v_mfma_f32_16x16x32_bf16 v[122:125], v[166:169], v[200:203], v[122:125]
	v_mfma_f32_16x16x32_bf16 v[118:121], v[174:177], v[200:203], v[118:121]
	v_mfma_f32_16x16x32_bf16 v[106:109], v[166:169], v[208:211], v[106:109]
	v_mfma_f32_16x16x32_bf16 v[102:105], v[174:177], v[208:211], v[102:105]
	v_mfma_f32_16x16x32_bf16 v[90:93], v[166:169], v[216:219], v[90:93]
	v_mfma_f32_16x16x32_bf16 v[86:89], v[174:177], v[216:219], v[86:89]
	v_mfma_f32_16x16x32_bf16 v[70:73], v[166:169], v[224:227], v[70:73]
	v_mfma_f32_16x16x32_bf16 v[66:69], v[174:177], v[224:227], v[66:69]
	v_mfma_f32_16x16x32_bf16 v[122:125], v[170:173], v[204:207], v[122:125]
	v_mfma_f32_16x16x32_bf16 v[118:121], v[182:185], v[204:207], v[118:121]
	v_mfma_f32_16x16x32_bf16 v[106:109], v[170:173], v[212:215], v[106:109]
	v_mfma_f32_16x16x32_bf16 v[102:105], v[182:185], v[212:215], v[102:105]
	v_mfma_f32_16x16x32_bf16 v[90:93], v[170:173], v[220:223], v[90:93]
	v_mfma_f32_16x16x32_bf16 v[86:89], v[182:185], v[220:223], v[86:89]
	v_mfma_f32_16x16x32_bf16 v[70:73], v[170:173], v[228:231], v[70:73]
	v_mfma_f32_16x16x32_bf16 v[66:69], v[182:185], v[228:231], v[66:69]
	s_barrier
	s_setprio 0
	s_add_i32 s80, s80, s36
	v_lshl_add_u64 v[186:187], s[76:77], 0, v[152:153]
	s_mov_b32 m0, s80
	ds_read_b128 v[200:203], v180 offset:16384
	ds_read_b128 v[204:207], v180 offset:17408
	ds_read_b128 v[208:211], v180 offset:18432
	ds_read_b128 v[212:215], v180 offset:19456
	ds_read_b128 v[216:219], v180 offset:20480
	ds_read_b128 v[220:223], v180 offset:21504
	ds_read_b128 v[224:227], v180 offset:22528
	ds_read_b128 v[228:231], v180 offset:23552
	global_load_lds_dwordx4 v[186:187], off
	s_add_i32 m0, s80, 0x2000
	s_add_u32 s80, s76, 0x40000
	v_lshl_add_u64 v[232:233], s[76:77], 0, v[156:157]
	s_addc_u32 s81, s77, 0
	s_add_i32 s86, s86, s36
	global_load_lds_dwordx4 v[232:233], off
	v_lshl_add_u64 v[234:235], s[80:81], 0, v[152:153]
	s_mov_b32 m0, s86
	v_lshl_add_u64 v[236:237], s[78:79], 0, v[154:155]
	global_load_lds_dwordx4 v[234:235], off
	v_lshl_add_u64 v[234:235], s[80:81], 0, v[156:157]
	s_add_i32 m0, s86, 0x2000
	s_nop 0
	global_load_lds_dwordx4 v[234:235], off
	v_lshl_add_u64 v[234:235], s[78:79], 0, v[150:151]
	s_mov_b32 m0, s37
	s_nop 0
	global_load_lds_dwordx4 v[234:235], off
	s_mov_b32 m0, s42
	s_nop 0
	global_load_lds_dwordx4 v[236:237], off
	s_waitcnt vmcnt(8)
	s_waitcnt lgkmcnt(0)
	s_setprio 1
	s_barrier
; #define PG8_STAGE(bufoff, gbase, voff) do { _Pragma("unroll") for (int _i = 0; _i < 2; ++_i) \
;         __builtin_amdgcn_global_load_lds((const unsigned*)((const char*)(gbase) + (voff)[_i]), (PG8_LAS unsigned*)(lds + (bufoff) + ldsw + _i * 8192), 16, 0, 0); } while (0)
; #define PG8_LDA(dst, b, h) do { _Pragma("unroll") for (int m = 0; m < 4; ++m) _Pragma("unroll") for (int k = 0; k < 2; ++k) dst[m][k] = *(const PG8_LAS bf16x8*)(lds + PG8_SA(b, h) + aoff + m * 2048 + k * 1024); } while (0)
; #define PG8_LDB(dst, b, h) do { _Pragma("unroll") for (int n = 0; n < 2; ++n) _Pragma("unroll") for (int k = 0; k < 2; ++k) dst[n][k] = *(const PG8_LAS bf16x8*)(lds + PG8_SB(b, h) + boff + n * 2048 + k * 1024); } while (0)
; #define PG8_MMA(ai, bj, At, Bt) do { __builtin_amdgcn_s_setprio(1); _Pragma("unroll") for (int m = 0; m < 4; ++m) _Pragma("unroll") for (int n = 0; n < 2; ++n) _Pragma("unroll") for (int k = 0; k < 2; ++k) \
;         acc[ai][bj][m][n] = __builtin_amdgcn_mfma_f32_16x16x32_bf16(Bt[n][k], At[m][k], acc[ai][bj][m][n], 0, 0, 0); __builtin_amdgcn_s_setprio(0); } while (0)
; #define PG8_WAIT_V(n) asm volatile("s_waitcnt vmcnt(" #n ")" ::: "memory")
; #define PG8_WAIT_L(n) asm volatile("s_waitcnt lgkmcnt(" #n ")" ::: "memory")
; #define PG8_BAR __builtin_amdgcn_s_barrier()
; #define PG8_SCHED __builtin_amdgcn_sched_barrier(0)
; template <class Epi, class Sched, bool ALIGN_EPI = false, bool SP2 = false>
; __device__ __forceinline__ void gemm_phase(PG8_LAS unsigned char* lds, const Gemm g, const Sched& S, const Epi& E) {
;     ...
;             PG8_WAIT_V(8); PG8_WAIT_L(0); PG8_BAR; PG8_MMA(1, 0, At, B0); PG8_MMA(1, 1, At, B1); PG8_BAR; PG8_SCHED;
;             PG8_LDB(B0, 1, 0); PG8_LDB(B1, 1, 1); PG8_SCHED; PG8_LDA(At, 1, 0); PG8_STAGE(PG8_SA(0, 1), a2 + hstep, voffA);
;             PG8_WAIT_V(8); PG8_WAIT_L(0); PG8_BAR; PG8_MMA(0, 0, At, B0); PG8_MMA(0, 1, At, B1); PG8_BAR; PG8_SCHED;
	v_mfma_f32_16x16x32_bf16 v[62:65], v[134:137], v[200:203], v[62:65]
	v_mfma_f32_16x16x32_bf16 v[58:61], v[142:145], v[200:203], v[58:61]
	v_mfma_f32_16x16x32_bf16 v[46:49], v[134:137], v[208:211], v[46:49]
	v_mfma_f32_16x16x32_bf16 v[42:45], v[142:145], v[208:211], v[42:45]
	v_mfma_f32_16x16x32_bf16 v[30:33], v[134:137], v[216:219], v[30:33]
	v_mfma_f32_16x16x32_bf16 v[26:29], v[142:145], v[216:219], v[26:29]
	v_mfma_f32_16x16x32_bf16 v[14:17], v[134:137], v[224:227], v[14:17]
	v_mfma_f32_16x16x32_bf16 v[10:13], v[142:145], v[224:227], v[10:13]
	v_mfma_f32_16x16x32_bf16 v[62:65], v[138:141], v[204:207], v[62:65]
	v_mfma_f32_16x16x32_bf16 v[58:61], v[146:149], v[204:207], v[58:61]
	v_mfma_f32_16x16x32_bf16 v[46:49], v[138:141], v[212:215], v[46:49]
	v_mfma_f32_16x16x32_bf16 v[42:45], v[146:149], v[212:215], v[42:45]
	v_mfma_f32_16x16x32_bf16 v[30:33], v[138:141], v[220:223], v[30:33]
	v_mfma_f32_16x16x32_bf16 v[26:29], v[146:149], v[220:223], v[26:29]
	v_mfma_f32_16x16x32_bf16 v[14:17], v[138:141], v[228:231], v[14:17]
	v_mfma_f32_16x16x32_bf16 v[10:13], v[146:149], v[228:231], v[10:13]
	v_mfma_f32_16x16x32_bf16 v[54:57], v[166:169], v[200:203], v[54:57]
	v_mfma_f32_16x16x32_bf16 v[50:53], v[174:177], v[200:203], v[50:53]
	v_mfma_f32_16x16x32_bf16 v[38:41], v[166:169], v[208:211], v[38:41]
	v_mfma_f32_16x16x32_bf16 v[34:37], v[174:177], v[208:211], v[34:37]
	v_mfma_f32_16x16x32_bf16 v[22:25], v[166:169], v[216:219], v[22:25]
	v_mfma_f32_16x16x32_bf16 v[18:21], v[174:177], v[216:219], v[18:21]
	v_mfma_f32_16x16x32_bf16 v[6:9], v[166:169], v[224:227], v[6:9]
	v_mfma_f32_16x16x32_bf16 v[2:5], v[174:177], v[224:227], v[2:5]
	v_mfma_f32_16x16x32_bf16 v[54:57], v[170:173], v[204:207], v[54:57]
	v_mfma_f32_16x16x32_bf16 v[50:53], v[182:185], v[204:207], v[50:53]
	v_mfma_f32_16x16x32_bf16 v[38:41], v[170:173], v[212:215], v[38:41]
	v_mfma_f32_16x16x32_bf16 v[34:37], v[182:185], v[212:215], v[34:37]
	v_mfma_f32_16x16x32_bf16 v[22:25], v[170:173], v[220:223], v[22:25]
	v_mfma_f32_16x16x32_bf16 v[18:21], v[182:185], v[220:223], v[18:21]
	v_mfma_f32_16x16x32_bf16 v[6:9], v[170:173], v[228:231], v[6:9]
	v_mfma_f32_16x16x32_bf16 v[2:5], v[182:185], v[228:231], v[2:5]
	s_barrier
	s_setprio 0
	s_add_i32 s80, 0, 0x18000
	s_add_i32 s81, 0, 0x1c000
	v_add_u32_e32 v146, s80, v159
	v_add_u32_e32 v182, s81, v159
	ds_read_b128 v[134:137], v146
	ds_read_b128 v[138:141], v146 offset:1024
	ds_read_b128 v[142:145], v146 offset:2048
	ds_read_b128 v[146:149], v146 offset:3072
	ds_read_b128 v[166:169], v182
	ds_read_b128 v[170:173], v182 offset:1024
	ds_read_b128 v[174:177], v182 offset:2048
	ds_read_b128 v[182:185], v182 offset:3072
	s_add_u32 s78, s78, 0x40000
	s_addc_u32 s79, s79, 0
	s_mov_b32 m0, s48
	v_lshl_add_u64 v[238:239], s[78:79], 0, v[150:151]
	ds_read_b128 v[200:203], v180 offset:32768
	ds_read_b128 v[204:207], v180 offset:33792
	ds_read_b128 v[208:211], v180 offset:34816
	ds_read_b128 v[212:215], v180 offset:35840
	ds_read_b128 v[216:219], v180 offset:36864
	ds_read_b128 v[220:223], v180 offset:37888
	ds_read_b128 v[224:227], v180 offset:38912
	ds_read_b128 v[228:231], v180 offset:39936
	global_load_lds_dwordx4 v[238:239], off
	v_lshl_add_u64 v[238:239], s[78:79], 0, v[154:155]
	s_mov_b32 m0, s49
	s_nop 0
	global_load_lds_dwordx4 v[238:239], off
	s_waitcnt vmcnt(8)
	s_waitcnt lgkmcnt(0)
	s_setprio 1
	s_barrier
	v_mfma_f32_16x16x32_bf16 v[130:133], v[134:137], v[200:203], v[130:133]
	v_mfma_f32_16x16x32_bf16 v[126:129], v[142:145], v[200:203], v[126:129]
	v_mfma_f32_16x16x32_bf16 v[114:117], v[134:137], v[208:211], v[114:117]
	v_mfma_f32_16x16x32_bf16 v[110:113], v[142:145], v[208:211], v[110:113]
	v_mfma_f32_16x16x32_bf16 v[98:101], v[134:137], v[216:219], v[98:101]
	v_mfma_f32_16x16x32_bf16 v[94:97], v[142:145], v[216:219], v[94:97]
	v_mfma_f32_16x16x32_bf16 v[78:81], v[134:137], v[224:227], v[78:81]
	v_mfma_f32_16x16x32_bf16 v[74:77], v[142:145], v[224:227], v[74:77]
	v_mfma_f32_16x16x32_bf16 v[130:133], v[138:141], v[204:207], v[130:133]
	v_mfma_f32_16x16x32_bf16 v[126:129], v[146:149], v[204:207], v[126:129]
	v_mfma_f32_16x16x32_bf16 v[114:117], v[138:141], v[212:215], v[114:117]
	v_mfma_f32_16x16x32_bf16 v[110:113], v[146:149], v[212:215], v[110:113]
	v_mfma_f32_16x16x32_bf16 v[98:101], v[138:141], v[220:223], v[98:101]
	v_mfma_f32_16x16x32_bf16 v[94:97], v[146:149], v[220:223], v[94:97]
	v_mfma_f32_16x16x32_bf16 v[78:81], v[138:141], v[228:231], v[78:81]
	v_mfma_f32_16x16x32_bf16 v[74:77], v[146:149], v[228:231], v[74:77]
	v_mfma_f32_16x16x32_bf16 v[122:125], v[166:169], v[200:203], v[122:125]
	v_mfma_f32_16x16x32_bf16 v[118:121], v[174:177], v[200:203], v[118:121]
	v_mfma_f32_16x16x32_bf16 v[106:109], v[166:169], v[208:211], v[106:109]
	v_mfma_f32_16x16x32_bf16 v[102:105], v[174:177], v[208:211], v[102:105]
	v_mfma_f32_16x16x32_bf16 v[90:93], v[166:169], v[216:219], v[90:93]
	v_mfma_f32_16x16x32_bf16 v[86:89], v[174:177], v[216:219], v[86:89]
	v_mfma_f32_16x16x32_bf16 v[70:73], v[166:169], v[224:227], v[70:73]
	v_mfma_f32_16x16x32_bf16 v[66:69], v[174:177], v[224:227], v[66:69]
	v_mfma_f32_16x16x32_bf16 v[122:125], v[170:173], v[204:207], v[122:125]
	v_mfma_f32_16x16x32_bf16 v[118:121], v[182:185], v[204:207], v[118:121]
	v_mfma_f32_16x16x32_bf16 v[106:109], v[170:173], v[212:215], v[106:109]
	v_mfma_f32_16x16x32_bf16 v[102:105], v[182:185], v[212:215], v[102:105]
	v_mfma_f32_16x16x32_bf16 v[90:93], v[170:173], v[220:223], v[90:93]
	v_mfma_f32_16x16x32_bf16 v[86:89], v[182:185], v[220:223], v[86:89]
	v_mfma_f32_16x16x32_bf16 v[70:73], v[170:173], v[228:231], v[70:73]
	v_mfma_f32_16x16x32_bf16 v[66:69], v[182:185], v[228:231], v[66:69]
	s_barrier
; #define PG8_STAGE(bufoff, gbase, voff) do { _Pragma("unroll") for (int _i = 0; _i < 2; ++_i) \
;         __builtin_amdgcn_global_load_lds((const unsigned*)((const char*)(gbase) + (voff)[_i]), (PG8_LAS unsigned*)(lds + (bufoff) + ldsw + _i * 8192), 16, 0, 0); } while (0)
; #define PG8_LDA(dst, b, h) do { _Pragma("unroll") for (int m = 0; m < 4; ++m) _Pragma("unroll") for (int k = 0; k < 2; ++k) dst[m][k] = *(const PG8_LAS bf16x8*)(lds + PG8_SA(b, h) + aoff + m * 2048 + k * 1024); } while (0)
; #define PG8_MMA(ai, bj, At, Bt) do { __builtin_amdgcn_s_setprio(1); _Pragma("unroll") for (int m = 0; m < 4; ++m) _Pragma("unroll") for (int n = 0; n < 2; ++n) _Pragma("unroll") for (int k = 0; k < 2; ++k) \
;         acc[ai][bj][m][n] = __builtin_amdgcn_mfma_f32_16x16x32_bf16(Bt[n][k], At[m][k], acc[ai][bj][m][n], 0, 0, 0); __builtin_amdgcn_s_setprio(0); } while (0)
; #define PG8_WAIT_V(n) asm volatile("s_waitcnt vmcnt(" #n ")" ::: "memory")
; #define PG8_WAIT_L(n) asm volatile("s_waitcnt lgkmcnt(" #n ")" ::: "memory")
; #define PG8_BAR __builtin_amdgcn_s_barrier()
; #define PG8_SCHED __builtin_amdgcn_sched_barrier(0)
; template <class Epi, class Sched, bool ALIGN_EPI = false, bool SP2 = false>
; __device__ __forceinline__ void gemm_phase(PG8_LAS unsigned char* lds, const Gemm g, const Sched& S, const Epi& E) {
;     ...
;         for (int t = 0; t < nt; t += 2) {
;             const bool last = (t == nt - 2);
;             const char* a1 = cA + (size_t)(t + 1) * kstep;
;             const char* a2 = last ? nA : cA + (size_t)(t + 2) * kstep; const char* b2 = last ? nB : cB + (size_t)(t + 2) * kstep;
;     ...
;             PG8_LDA(At, 1, 1); PG8_STAGE(PG8_SB(1, 0), b3, voffB); PG8_STAGE(PG8_SB(1, 1), b3 + hstep, voffB); PG8_STAGE(PG8_SA(1, 0), a3, voffA);
;             PG8_WAIT_V(8); PG8_WAIT_L(0); PG8_BAR; PG8_MMA(1, 0, At, B0); PG8_MMA(1, 1, At, B1); PG8_BAR; PG8_SCHED;
	s_setprio 0
	s_add_i32 s78, s80, s36
	v_lshl_add_u64 v[186:187], v[186:187], 0, s[38:39]
	s_mov_b32 m0, s78
	ds_read_b128 v[200:203], v180 offset:49152
	ds_read_b128 v[204:207], v180 offset:50176
	ds_read_b128 v[208:211], v180 offset:51200
	ds_read_b128 v[212:215], v180 offset:52224
	ds_read_b128 v[216:219], v180 offset:53248
	ds_read_b128 v[220:223], v180 offset:54272
	ds_read_b128 v[224:227], v180 offset:55296
	ds_read_b128 v[228:231], v180 offset:56320
	global_load_lds_dwordx4 v[186:187], off
	s_add_i32 m0, s78, 0x2000
	s_add_u32 s76, s76, 0x40080
	v_lshl_add_u64 v[186:187], v[232:233], 0, s[38:39]
	s_addc_u32 s77, s77, 0
	s_add_i32 s78, s81, s36
	global_load_lds_dwordx4 v[186:187], off
	v_lshl_add_u64 v[186:187], s[76:77], 0, v[152:153]
	s_mov_b32 m0, s78
	s_nop 0
	global_load_lds_dwordx4 v[186:187], off
	v_lshl_add_u64 v[186:187], s[76:77], 0, v[156:157]
	s_add_i32 m0, s78, 0x2000
	s_nop 0
	global_load_lds_dwordx4 v[186:187], off
	v_lshl_add_u64 v[186:187], v[234:235], 0, s[38:39]
	s_mov_b32 m0, s56
	s_nop 0
	global_load_lds_dwordx4 v[186:187], off
	v_lshl_add_u64 v[186:187], v[236:237], 0, s[38:39]
	s_mov_b32 m0, s75
	s_nop 0
	global_load_lds_dwordx4 v[186:187], off
	s_waitcnt vmcnt(8)
	s_waitcnt lgkmcnt(0)
	s_setprio 1
	s_barrier
	v_mfma_f32_16x16x32_bf16 v[62:65], v[134:137], v[200:203], v[62:65]
	v_mfma_f32_16x16x32_bf16 v[58:61], v[142:145], v[200:203], v[58:61]
	v_mfma_f32_16x16x32_bf16 v[46:49], v[134:137], v[208:211], v[46:49]
	v_mfma_f32_16x16x32_bf16 v[42:45], v[142:145], v[208:211], v[42:45]
	v_mfma_f32_16x16x32_bf16 v[30:33], v[134:137], v[216:219], v[30:33]
	v_mfma_f32_16x16x32_bf16 v[26:29], v[142:145], v[216:219], v[26:29]
	v_mfma_f32_16x16x32_bf16 v[14:17], v[134:137], v[224:227], v[14:17]
	v_mfma_f32_16x16x32_bf16 v[10:13], v[142:145], v[224:227], v[10:13]
	v_mfma_f32_16x16x32_bf16 v[62:65], v[138:141], v[204:207], v[62:65]
	v_mfma_f32_16x16x32_bf16 v[58:61], v[146:149], v[204:207], v[58:61]
	v_mfma_f32_16x16x32_bf16 v[46:49], v[138:141], v[212:215], v[46:49]
	v_mfma_f32_16x16x32_bf16 v[42:45], v[146:149], v[212:215], v[42:45]
	v_mfma_f32_16x16x32_bf16 v[30:33], v[138:141], v[220:223], v[30:33]
	v_mfma_f32_16x16x32_bf16 v[26:29], v[146:149], v[220:223], v[26:29]
	v_mfma_f32_16x16x32_bf16 v[14:17], v[138:141], v[228:231], v[14:17]
	v_mfma_f32_16x16x32_bf16 v[10:13], v[146:149], v[228:231], v[10:13]
	v_mfma_f32_16x16x32_bf16 v[54:57], v[166:169], v[200:203], v[54:57]
	v_mfma_f32_16x16x32_bf16 v[50:53], v[174:177], v[200:203], v[50:53]
	v_mfma_f32_16x16x32_bf16 v[38:41], v[166:169], v[208:211], v[38:41]
	v_mfma_f32_16x16x32_bf16 v[34:37], v[174:177], v[208:211], v[34:37]
	v_mfma_f32_16x16x32_bf16 v[22:25], v[166:169], v[216:219], v[22:25]
	v_mfma_f32_16x16x32_bf16 v[18:21], v[174:177], v[216:219], v[18:21]
	v_mfma_f32_16x16x32_bf16 v[6:9], v[166:169], v[224:227], v[6:9]
	v_mfma_f32_16x16x32_bf16 v[2:5], v[174:177], v[224:227], v[2:5]
	v_mfma_f32_16x16x32_bf16 v[54:57], v[170:173], v[204:207], v[54:57]
	v_mfma_f32_16x16x32_bf16 v[50:53], v[182:185], v[204:207], v[50:53]
	v_mfma_f32_16x16x32_bf16 v[38:41], v[170:173], v[212:215], v[38:41]
	v_mfma_f32_16x16x32_bf16 v[34:37], v[182:185], v[212:215], v[34:37]
	v_mfma_f32_16x16x32_bf16 v[22:25], v[170:173], v[220:223], v[22:25]
	v_mfma_f32_16x16x32_bf16 v[18:21], v[182:185], v[220:223], v[18:21]
	v_mfma_f32_16x16x32_bf16 v[6:9], v[170:173], v[228:231], v[6:9]
	v_mfma_f32_16x16x32_bf16 v[2:5], v[182:185], v[228:231], v[2:5]
	s_barrier
	s_setprio 0
	s_add_i32 s69, s69, 2
	s_add_u32 s41, s41, 0x100
	s_addc_u32 s67, s67, 0
	s_add_u32 s12, s12, 0x100
	s_addc_u32 s13, s13, 0
	s_cmp_gt_u32 s69, 13
	s_cbranch_scc0 .LBB0_111
	s_and_b64 vcc, exec, s[64:65]
	s_cbranch_vccz .LBB0_114
	s_barrier

; #define PG8_STAGE(bufoff, gbase, voff) do { _Pragma("unroll") for (int _i = 0; _i < 2; ++_i) \
;         __builtin_amdgcn_global_load_lds((const unsigned*)((const char*)(gbase) + (voff)[_i]), (PG8_LAS unsigned*)(lds + (bufoff) + ldsw + _i * 8192), 16, 0, 0); } while (0)
; #define PG8_LDA(dst, b, h) do { _Pragma("unroll") for (int m = 0; m < 4; ++m) _Pragma("unroll") for (int k = 0; k < 2; ++k) dst[m][k] = *(const PG8_LAS bf16x8*)(lds + PG8_SA(b, h) + aoff + m * 2048 + k * 1024); } while (0)
; #define PG8_LDB(dst, b, h) do { _Pragma("unroll") for (int n = 0; n < 2; ++n) _Pragma("unroll") for (int k = 0; k < 2; ++k) dst[n][k] = *(const PG8_LAS bf16x8*)(lds + PG8_SB(b, h) + boff + n * 2048 + k * 1024); } while (0)
; #define PG8_MMA(ai, bj, At, Bt) do { __builtin_amdgcn_s_setprio(1); _Pragma("unroll") for (int m = 0; m < 4; ++m) _Pragma("unroll") for (int n = 0; n < 2; ++n) _Pragma("unroll") for (int k = 0; k < 2; ++k) \
;         acc[ai][bj][m][n] = __builtin_amdgcn_mfma_f32_16x16x32_bf16(Bt[n][k], At[m][k], acc[ai][bj][m][n], 0, 0, 0); __builtin_amdgcn_s_setprio(0); } while (0)
; #define PG8_WAIT_V(n) asm volatile("s_waitcnt vmcnt(" #n ")" ::: "memory")
; #define PG8_WAIT_L(n) asm volatile("s_waitcnt lgkmcnt(" #n ")" ::: "memory")
; #define PG8_BAR __builtin_amdgcn_s_barrier()
; #define PG8_SCHED __builtin_amdgcn_sched_barrier(0)
; template <class Epi, class Sched, bool ALIGN_EPI = false, bool SP2 = false>
; __device__ __forceinline__ void gemm_phase(PG8_LAS unsigned char* lds, const Gemm g, const Sched& S, const Epi& E) {
;     ...
;             const bool last = (t == nt - 2);
;             const char* a1 = cA + (size_t)(t + 1) * kstep;
;             const char* a2 = last ? nA : cA + (size_t)(t + 2) * kstep; const char* b2 = last ? nB : cB + (size_t)(t + 2) * kstep;
;             const char* a3 = a2 + kstep; const char* b3 = b2 + kstep;
;             if (last && has_next) S.a_ready(nxt);
;             if constexpr (SP2) {
;             PG8_LDB(B0, 0, 0); PG8_LDB(B1, 0, 1); PG8_SCHED; PG8_LDA(At, 0, 0); PG8_STAGE(PG8_SA(1, 1), a1 + hstep, voffA);
;             PG8_WAIT_V(8); PG8_WAIT_L(0); PG8_BAR; PG8_MMA(0, 0, At, B0); PG8_MMA(0, 1, At, B1); PG8_BAR; PG8_SCHED;
;             PG8_LDA(At, 0, 1); PG8_STAGE(PG8_SB(0, 0), b2, voffB); PG8_STAGE(PG8_SB(0, 1), b2 + hstep, voffB); PG8_STAGE(PG8_SA(0, 0), a2, voffA);
.LBB0_684:
	s_add_u32 s24, s20, 0x100
	s_addc_u32 s25, s21, 0
	s_add_i32 s63, 0, 0x10000
	s_cmp_eq_u32 s62, 16
	s_cselect_b32 s59, s7, s25
	s_cselect_b32 s58, s6, s24
	v_add_u32_e32 v150, s63, v152
	s_cselect_b32 s27, s19, s61
	s_cselect_b32 s26, s18, s41
	s_add_i32 s64, 0, 0x14000
	ds_read_b128 v[146:149], v150
	ds_read_b128 v[156:159], v150 offset:1024
	ds_read_b128 v[160:163], v150 offset:2048
	ds_read_b128 v[164:167], v150 offset:3072
	v_add_u32_e32 v150, s64, v152
	ds_read_b128 v[168:171], v150
	ds_read_b128 v[172:175], v150 offset:1024
	ds_read_b128 v[180:183], v150 offset:2048
	ds_read_b128 v[184:187], v150 offset:3072
	v_lshl_add_u64 v[150:151], s[20:21], 0, v[144:145]
	s_add_i32 m0, s42, 0xc000
	ds_read_b128 v[200:203], v154
	ds_read_b128 v[204:207], v154 offset:1024
	ds_read_b128 v[208:211], v154 offset:2048
	ds_read_b128 v[212:215], v154 offset:3072
	ds_read_b128 v[216:219], v154 offset:4096
	ds_read_b128 v[220:223], v154 offset:5120
	ds_read_b128 v[224:227], v154 offset:6144
	ds_read_b128 v[228:231], v154 offset:7168
	global_load_lds_dwordx4 v[150:151], off
	v_lshl_add_u64 v[150:151], s[20:21], 0, v[142:143]
	s_add_i32 m0, s42, 0xe000
	s_nop 0
	global_load_lds_dwordx4 v[150:151], off
	s_waitcnt vmcnt(8)
	s_waitcnt lgkmcnt(0)
	s_setprio 1
	s_barrier
	v_mfma_f32_16x16x32_bf16 v[130:133], v[146:149], v[200:203], v[130:133]
	v_mfma_f32_16x16x32_bf16 v[126:129], v[160:163], v[200:203], v[126:129]
	v_mfma_f32_16x16x32_bf16 v[114:117], v[146:149], v[208:211], v[114:117]
	v_mfma_f32_16x16x32_bf16 v[110:113], v[160:163], v[208:211], v[110:113]
	v_mfma_f32_16x16x32_bf16 v[98:101], v[146:149], v[216:219], v[98:101]
	v_mfma_f32_16x16x32_bf16 v[94:97], v[160:163], v[216:219], v[94:97]
	v_mfma_f32_16x16x32_bf16 v[78:81], v[146:149], v[224:227], v[78:81]
	v_mfma_f32_16x16x32_bf16 v[74:77], v[160:163], v[224:227], v[74:77]
	v_mfma_f32_16x16x32_bf16 v[130:133], v[156:159], v[204:207], v[130:133]
	v_mfma_f32_16x16x32_bf16 v[126:129], v[164:167], v[204:207], v[126:129]
	v_mfma_f32_16x16x32_bf16 v[114:117], v[156:159], v[212:215], v[114:117]
	v_mfma_f32_16x16x32_bf16 v[110:113], v[164:167], v[212:215], v[110:113]
	v_mfma_f32_16x16x32_bf16 v[98:101], v[156:159], v[220:223], v[98:101]
	v_mfma_f32_16x16x32_bf16 v[94:97], v[164:167], v[220:223], v[94:97]
	v_mfma_f32_16x16x32_bf16 v[78:81], v[156:159], v[228:231], v[78:81]
	v_mfma_f32_16x16x32_bf16 v[74:77], v[164:167], v[228:231], v[74:77]
	v_mfma_f32_16x16x32_bf16 v[122:125], v[168:171], v[200:203], v[122:125]
	v_mfma_f32_16x16x32_bf16 v[118:121], v[180:183], v[200:203], v[118:121]
	v_mfma_f32_16x16x32_bf16 v[106:109], v[168:171], v[208:211], v[106:109]
	v_mfma_f32_16x16x32_bf16 v[102:105], v[180:183], v[208:211], v[102:105]
	v_mfma_f32_16x16x32_bf16 v[90:93], v[168:171], v[216:219], v[90:93]
	v_mfma_f32_16x16x32_bf16 v[86:89], v[180:183], v[216:219], v[86:89]
	v_mfma_f32_16x16x32_bf16 v[70:73], v[168:171], v[224:227], v[70:73]
	v_mfma_f32_16x16x32_bf16 v[66:69], v[180:183], v[224:227], v[66:69]
	v_mfma_f32_16x16x32_bf16 v[122:125], v[172:175], v[204:207], v[122:125]
	v_mfma_f32_16x16x32_bf16 v[118:121], v[184:187], v[204:207], v[118:121]
	v_mfma_f32_16x16x32_bf16 v[106:109], v[172:175], v[212:215], v[106:109]
	v_mfma_f32_16x16x32_bf16 v[102:105], v[184:187], v[212:215], v[102:105]
	v_mfma_f32_16x16x32_bf16 v[90:93], v[172:175], v[220:223], v[90:93]
	v_mfma_f32_16x16x32_bf16 v[86:89], v[184:187], v[220:223], v[86:89]
	v_mfma_f32_16x16x32_bf16 v[70:73], v[172:175], v[228:231], v[70:73]
	v_mfma_f32_16x16x32_bf16 v[66:69], v[184:187], v[228:231], v[66:69]
	s_barrier
	s_setprio 0
	s_add_i32 s20, s63, s29
	v_lshl_add_u64 v[150:151], s[26:27], 0, v[138:139]
	s_mov_b32 m0, s20
	ds_read_b128 v[200:203], v154 offset:16384
	ds_read_b128 v[204:207], v154 offset:17408
	ds_read_b128 v[208:211], v154 offset:18432
	ds_read_b128 v[212:215], v154 offset:19456
	ds_read_b128 v[216:219], v154 offset:20480
	ds_read_b128 v[220:223], v154 offset:21504
	ds_read_b128 v[224:227], v154 offset:22528
	ds_read_b128 v[228:231], v154 offset:23552
	global_load_lds_dwordx4 v[150:151], off
	s_add_i32 m0, s20, 0x2000
	s_add_u32 s20, s26, 0x50000
	v_lshl_add_u64 v[176:177], s[26:27], 0, v[134:135]
	s_addc_u32 s21, s27, 0
	s_add_i32 s63, s64, s29
	global_load_lds_dwordx4 v[176:177], off
	v_lshl_add_u64 v[232:233], s[20:21], 0, v[138:139]
	s_mov_b32 m0, s63
	v_lshl_add_u64 v[234:235], s[58:59], 0, v[136:137]
	global_load_lds_dwordx4 v[232:233], off
	v_lshl_add_u64 v[232:233], s[20:21], 0, v[134:135]
	s_add_i32 m0, s63, 0x2000
	s_nop 0
	global_load_lds_dwordx4 v[232:233], off
	v_lshl_add_u64 v[232:233], s[58:59], 0, v[140:141]
	s_mov_b32 m0, s42
	s_nop 0
	global_load_lds_dwordx4 v[232:233], off
	s_mov_b32 m0, s48
	s_nop 0
	global_load_lds_dwordx4 v[234:235], off
	s_waitcnt vmcnt(8)
	s_waitcnt lgkmcnt(0)
	s_setprio 1
	s_barrier
; #define PG8_STAGE(bufoff, gbase, voff) do { _Pragma("unroll") for (int _i = 0; _i < 2; ++_i) \
;         __builtin_amdgcn_global_load_lds((const unsigned*)((const char*)(gbase) + (voff)[_i]), (PG8_LAS unsigned*)(lds + (bufoff) + ldsw + _i * 8192), 16, 0, 0); } while (0)
; #define PG8_LDA(dst, b, h) do { _Pragma("unroll") for (int m = 0; m < 4; ++m) _Pragma("unroll") for (int k = 0; k < 2; ++k) dst[m][k] = *(const PG8_LAS bf16x8*)(lds + PG8_SA(b, h) + aoff + m * 2048 + k * 1024); } while (0)
; #define PG8_LDB(dst, b, h) do { _Pragma("unroll") for (int n = 0; n < 2; ++n) _Pragma("unroll") for (int k = 0; k < 2; ++k) dst[n][k] = *(const PG8_LAS bf16x8*)(lds + PG8_SB(b, h) + boff + n * 2048 + k * 1024); } while (0)
; #define PG8_MMA(ai, bj, At, Bt) do { __builtin_amdgcn_s_setprio(1); _Pragma("unroll") for (int m = 0; m < 4; ++m) _Pragma("unroll") for (int n = 0; n < 2; ++n) _Pragma("unroll") for (int k = 0; k < 2; ++k) \
;         acc[ai][bj][m][n] = __builtin_amdgcn_mfma_f32_16x16x32_bf16(Bt[n][k], At[m][k], acc[ai][bj][m][n], 0, 0, 0); __builtin_amdgcn_s_setprio(0); } while (0)
; #define PG8_WAIT_V(n) asm volatile("s_waitcnt vmcnt(" #n ")" ::: "memory")
; #define PG8_WAIT_L(n) asm volatile("s_waitcnt lgkmcnt(" #n ")" ::: "memory")
; #define PG8_BAR __builtin_amdgcn_s_barrier()
; #define PG8_SCHED __builtin_amdgcn_sched_barrier(0)
; template <class Epi, class Sched, bool ALIGN_EPI = false, bool SP2 = false>
; __device__ __forceinline__ void gemm_phase(PG8_LAS unsigned char* lds, const Gemm g, const Sched& S, const Epi& E) {
;     ...
;             PG8_WAIT_V(8); PG8_WAIT_L(0); PG8_BAR; PG8_MMA(1, 0, At, B0); PG8_MMA(1, 1, At, B1); PG8_BAR; PG8_SCHED;
;             PG8_LDB(B0, 1, 0); PG8_LDB(B1, 1, 1); PG8_SCHED; PG8_LDA(At, 1, 0); PG8_STAGE(PG8_SA(0, 1), a2 + hstep, voffA);
;             PG8_WAIT_V(8); PG8_WAIT_L(0); PG8_BAR; PG8_MMA(0, 0, At, B0); PG8_MMA(0, 1, At, B1); PG8_BAR; PG8_SCHED;
	v_mfma_f32_16x16x32_bf16 v[62:65], v[146:149], v[200:203], v[62:65]
	v_mfma_f32_16x16x32_bf16 v[58:61], v[160:163], v[200:203], v[58:61]
	v_mfma_f32_16x16x32_bf16 v[46:49], v[146:149], v[208:211], v[46:49]
	v_mfma_f32_16x16x32_bf16 v[42:45], v[160:163], v[208:211], v[42:45]
	v_mfma_f32_16x16x32_bf16 v[30:33], v[146:149], v[216:219], v[30:33]
	v_mfma_f32_16x16x32_bf16 v[26:29], v[160:163], v[216:219], v[26:29]
	v_mfma_f32_16x16x32_bf16 v[14:17], v[146:149], v[224:227], v[14:17]
	v_mfma_f32_16x16x32_bf16 v[10:13], v[160:163], v[224:227], v[10:13]
	v_mfma_f32_16x16x32_bf16 v[62:65], v[156:159], v[204:207], v[62:65]
	v_mfma_f32_16x16x32_bf16 v[58:61], v[164:167], v[204:207], v[58:61]
	v_mfma_f32_16x16x32_bf16 v[46:49], v[156:159], v[212:215], v[46:49]
	v_mfma_f32_16x16x32_bf16 v[42:45], v[164:167], v[212:215], v[42:45]
	v_mfma_f32_16x16x32_bf16 v[30:33], v[156:159], v[220:223], v[30:33]
	v_mfma_f32_16x16x32_bf16 v[26:29], v[164:167], v[220:223], v[26:29]
	v_mfma_f32_16x16x32_bf16 v[14:17], v[156:159], v[228:231], v[14:17]
	v_mfma_f32_16x16x32_bf16 v[10:13], v[164:167], v[228:231], v[10:13]
	v_mfma_f32_16x16x32_bf16 v[54:57], v[168:171], v[200:203], v[54:57]
	v_mfma_f32_16x16x32_bf16 v[50:53], v[180:183], v[200:203], v[50:53]
	v_mfma_f32_16x16x32_bf16 v[38:41], v[168:171], v[208:211], v[38:41]
	v_mfma_f32_16x16x32_bf16 v[34:37], v[180:183], v[208:211], v[34:37]
	v_mfma_f32_16x16x32_bf16 v[22:25], v[168:171], v[216:219], v[22:25]
	v_mfma_f32_16x16x32_bf16 v[18:21], v[180:183], v[216:219], v[18:21]
	v_mfma_f32_16x16x32_bf16 v[6:9], v[168:171], v[224:227], v[6:9]
	v_mfma_f32_16x16x32_bf16 v[2:5], v[180:183], v[224:227], v[2:5]
	v_mfma_f32_16x16x32_bf16 v[54:57], v[172:175], v[204:207], v[54:57]
	v_mfma_f32_16x16x32_bf16 v[50:53], v[184:187], v[204:207], v[50:53]
	v_mfma_f32_16x16x32_bf16 v[38:41], v[172:175], v[212:215], v[38:41]
	v_mfma_f32_16x16x32_bf16 v[34:37], v[184:187], v[212:215], v[34:37]
	v_mfma_f32_16x16x32_bf16 v[22:25], v[172:175], v[220:223], v[22:25]
	v_mfma_f32_16x16x32_bf16 v[18:21], v[184:187], v[220:223], v[18:21]
	v_mfma_f32_16x16x32_bf16 v[6:9], v[172:175], v[228:231], v[6:9]
	v_mfma_f32_16x16x32_bf16 v[2:5], v[184:187], v[228:231], v[2:5]
	s_barrier
	s_setprio 0
	s_add_i32 s63, 0, 0x18000
	v_add_u32_e32 v155, s63, v152
	s_add_i32 s64, 0, 0x1c000
	ds_read_b128 v[146:149], v155
	ds_read_b128 v[156:159], v155 offset:1024
	ds_read_b128 v[160:163], v155 offset:2048
	ds_read_b128 v[164:167], v155 offset:3072
	v_add_u32_e32 v155, s64, v152
	ds_read_b128 v[168:171], v155
	ds_read_b128 v[172:175], v155 offset:1024
	ds_read_b128 v[180:183], v155 offset:2048
	ds_read_b128 v[184:187], v155 offset:3072
	s_add_u32 s20, s58, 0x50000
	s_addc_u32 s21, s59, 0
	s_mov_b32 m0, s49
	v_lshl_add_u64 v[236:237], s[20:21], 0, v[140:141]
	ds_read_b128 v[200:203], v154 offset:32768
	ds_read_b128 v[204:207], v154 offset:33792
	ds_read_b128 v[208:211], v154 offset:34816
	ds_read_b128 v[212:215], v154 offset:35840
	ds_read_b128 v[216:219], v154 offset:36864
	ds_read_b128 v[220:223], v154 offset:37888
	ds_read_b128 v[224:227], v154 offset:38912
	ds_read_b128 v[228:231], v154 offset:39936
	global_load_lds_dwordx4 v[236:237], off
	v_lshl_add_u64 v[236:237], s[20:21], 0, v[136:137]
	s_mov_b32 m0, s52
	s_nop 0
	global_load_lds_dwordx4 v[236:237], off
	s_waitcnt vmcnt(8)
	s_waitcnt lgkmcnt(0)
	s_setprio 1
	s_barrier
	v_mfma_f32_16x16x32_bf16 v[130:133], v[146:149], v[200:203], v[130:133]
	v_mfma_f32_16x16x32_bf16 v[126:129], v[160:163], v[200:203], v[126:129]
	v_mfma_f32_16x16x32_bf16 v[114:117], v[146:149], v[208:211], v[114:117]
	v_mfma_f32_16x16x32_bf16 v[110:113], v[160:163], v[208:211], v[110:113]
	v_mfma_f32_16x16x32_bf16 v[98:101], v[146:149], v[216:219], v[98:101]
	v_mfma_f32_16x16x32_bf16 v[94:97], v[160:163], v[216:219], v[94:97]
	v_mfma_f32_16x16x32_bf16 v[78:81], v[146:149], v[224:227], v[78:81]
	v_mfma_f32_16x16x32_bf16 v[74:77], v[160:163], v[224:227], v[74:77]
	v_mfma_f32_16x16x32_bf16 v[130:133], v[156:159], v[204:207], v[130:133]
	v_mfma_f32_16x16x32_bf16 v[126:129], v[164:167], v[204:207], v[126:129]
	v_mfma_f32_16x16x32_bf16 v[114:117], v[156:159], v[212:215], v[114:117]
	v_mfma_f32_16x16x32_bf16 v[110:113], v[164:167], v[212:215], v[110:113]
	v_mfma_f32_16x16x32_bf16 v[98:101], v[156:159], v[220:223], v[98:101]
	v_mfma_f32_16x16x32_bf16 v[94:97], v[164:167], v[220:223], v[94:97]
	v_mfma_f32_16x16x32_bf16 v[78:81], v[156:159], v[228:231], v[78:81]
	v_mfma_f32_16x16x32_bf16 v[74:77], v[164:167], v[228:231], v[74:77]
	v_mfma_f32_16x16x32_bf16 v[122:125], v[168:171], v[200:203], v[122:125]
	v_mfma_f32_16x16x32_bf16 v[118:121], v[180:183], v[200:203], v[118:121]
	v_mfma_f32_16x16x32_bf16 v[106:109], v[168:171], v[208:211], v[106:109]
	v_mfma_f32_16x16x32_bf16 v[102:105], v[180:183], v[208:211], v[102:105]
	v_mfma_f32_16x16x32_bf16 v[90:93], v[168:171], v[216:219], v[90:93]
	v_mfma_f32_16x16x32_bf16 v[86:89], v[180:183], v[216:219], v[86:89]
	v_mfma_f32_16x16x32_bf16 v[70:73], v[168:171], v[224:227], v[70:73]
	v_mfma_f32_16x16x32_bf16 v[66:69], v[180:183], v[224:227], v[66:69]
	v_mfma_f32_16x16x32_bf16 v[122:125], v[172:175], v[204:207], v[122:125]
	v_mfma_f32_16x16x32_bf16 v[118:121], v[184:187], v[204:207], v[118:121]
	v_mfma_f32_16x16x32_bf16 v[106:109], v[172:175], v[212:215], v[106:109]
	v_mfma_f32_16x16x32_bf16 v[102:105], v[184:187], v[212:215], v[102:105]
	v_mfma_f32_16x16x32_bf16 v[90:93], v[172:175], v[220:223], v[90:93]
	v_mfma_f32_16x16x32_bf16 v[86:89], v[184:187], v[220:223], v[86:89]
	v_mfma_f32_16x16x32_bf16 v[70:73], v[172:175], v[228:231], v[70:73]
	v_mfma_f32_16x16x32_bf16 v[66:69], v[184:187], v[228:231], v[66:69]
	s_barrier
; #define PG8_STAGE(bufoff, gbase, voff) do { _Pragma("unroll") for (int _i = 0; _i < 2; ++_i) \
;         __builtin_amdgcn_global_load_lds((const unsigned*)((const char*)(gbase) + (voff)[_i]), (PG8_LAS unsigned*)(lds + (bufoff) + ldsw + _i * 8192), 16, 0, 0); } while (0)
; #define PG8_LDA(dst, b, h) do { _Pragma("unroll") for (int m = 0; m < 4; ++m) _Pragma("unroll") for (int k = 0; k < 2; ++k) dst[m][k] = *(const PG8_LAS bf16x8*)(lds + PG8_SA(b, h) + aoff + m * 2048 + k * 1024); } while (0)
; #define PG8_MMA(ai, bj, At, Bt) do { __builtin_amdgcn_s_setprio(1); _Pragma("unroll") for (int m = 0; m < 4; ++m) _Pragma("unroll") for (int n = 0; n < 2; ++n) _Pragma("unroll") for (int k = 0; k < 2; ++k) \
;         acc[ai][bj][m][n] = __builtin_amdgcn_mfma_f32_16x16x32_bf16(Bt[n][k], At[m][k], acc[ai][bj][m][n], 0, 0, 0); __builtin_amdgcn_s_setprio(0); } while (0)
; #define PG8_WAIT_V(n) asm volatile("s_waitcnt vmcnt(" #n ")" ::: "memory")
; #define PG8_WAIT_L(n) asm volatile("s_waitcnt lgkmcnt(" #n ")" ::: "memory")
; #define PG8_BAR __builtin_amdgcn_s_barrier()
; #define PG8_SCHED __builtin_amdgcn_sched_barrier(0)
; template <class Epi, class Sched, bool ALIGN_EPI = false, bool SP2 = false>
; __device__ __forceinline__ void gemm_phase(PG8_LAS unsigned char* lds, const Gemm g, const Sched& S, const Epi& E) {
;     ...
;         for (int t = 0; t < nt; t += 2) {
;             const bool last = (t == nt - 2);
;             const char* a1 = cA + (size_t)(t + 1) * kstep;
;             const char* a2 = last ? nA : cA + (size_t)(t + 2) * kstep; const char* b2 = last ? nB : cB + (size_t)(t + 2) * kstep;
;     ...
;             PG8_LDA(At, 1, 1); PG8_STAGE(PG8_SB(1, 0), b3, voffB); PG8_STAGE(PG8_SB(1, 1), b3 + hstep, voffB); PG8_STAGE(PG8_SA(1, 0), a3, voffA);
;             PG8_WAIT_V(8); PG8_WAIT_L(0); PG8_BAR; PG8_MMA(1, 0, At, B0); PG8_MMA(1, 1, At, B1); PG8_BAR; PG8_SCHED;
	s_setprio 0
	s_add_i32 s20, s63, s29
	v_lshl_add_u64 v[150:151], v[150:151], 0, s[38:39]
	s_mov_b32 m0, s20
	ds_read_b128 v[200:203], v154 offset:49152
	ds_read_b128 v[204:207], v154 offset:50176
	ds_read_b128 v[208:211], v154 offset:51200
	ds_read_b128 v[212:215], v154 offset:52224
	ds_read_b128 v[216:219], v154 offset:53248
	ds_read_b128 v[220:223], v154 offset:54272
	ds_read_b128 v[224:227], v154 offset:55296
	ds_read_b128 v[228:231], v154 offset:56320
	global_load_lds_dwordx4 v[150:151], off
	s_add_i32 m0, s20, 0x2000
	s_add_u32 s20, s26, 0x50080
	v_lshl_add_u64 v[150:151], v[176:177], 0, s[38:39]
	s_addc_u32 s21, s27, 0
	s_add_i32 s26, s64, s29
	global_load_lds_dwordx4 v[150:151], off
	v_lshl_add_u64 v[150:151], s[20:21], 0, v[138:139]
	s_mov_b32 m0, s26
	s_nop 0
	global_load_lds_dwordx4 v[150:151], off
	v_lshl_add_u64 v[150:151], s[20:21], 0, v[134:135]
	s_add_i32 m0, s26, 0x2000
	s_nop 0
	global_load_lds_dwordx4 v[150:151], off
	v_lshl_add_u64 v[150:151], v[232:233], 0, s[38:39]
	s_mov_b32 m0, s53
	s_nop 0
	global_load_lds_dwordx4 v[150:151], off
	v_lshl_add_u64 v[150:151], v[234:235], 0, s[38:39]
	s_mov_b32 m0, s54
	s_nop 0
	global_load_lds_dwordx4 v[150:151], off
	s_waitcnt vmcnt(8)
	s_waitcnt lgkmcnt(0)
	s_setprio 1
	s_barrier
	v_mfma_f32_16x16x32_bf16 v[62:65], v[146:149], v[200:203], v[62:65]
	v_mfma_f32_16x16x32_bf16 v[58:61], v[160:163], v[200:203], v[58:61]
	v_mfma_f32_16x16x32_bf16 v[46:49], v[146:149], v[208:211], v[46:49]
	v_mfma_f32_16x16x32_bf16 v[42:45], v[160:163], v[208:211], v[42:45]
	v_mfma_f32_16x16x32_bf16 v[30:33], v[146:149], v[216:219], v[30:33]
	v_mfma_f32_16x16x32_bf16 v[26:29], v[160:163], v[216:219], v[26:29]
	v_mfma_f32_16x16x32_bf16 v[14:17], v[146:149], v[224:227], v[14:17]
	v_mfma_f32_16x16x32_bf16 v[10:13], v[160:163], v[224:227], v[10:13]
	v_mfma_f32_16x16x32_bf16 v[62:65], v[156:159], v[204:207], v[62:65]
	v_mfma_f32_16x16x32_bf16 v[58:61], v[164:167], v[204:207], v[58:61]
	v_mfma_f32_16x16x32_bf16 v[46:49], v[156:159], v[212:215], v[46:49]
	v_mfma_f32_16x16x32_bf16 v[42:45], v[164:167], v[212:215], v[42:45]
	v_mfma_f32_16x16x32_bf16 v[30:33], v[156:159], v[220:223], v[30:33]
	v_mfma_f32_16x16x32_bf16 v[26:29], v[164:167], v[220:223], v[26:29]
	v_mfma_f32_16x16x32_bf16 v[14:17], v[156:159], v[228:231], v[14:17]
	v_mfma_f32_16x16x32_bf16 v[10:13], v[164:167], v[228:231], v[10:13]
	v_mfma_f32_16x16x32_bf16 v[54:57], v[168:171], v[200:203], v[54:57]
	v_mfma_f32_16x16x32_bf16 v[50:53], v[180:183], v[200:203], v[50:53]
	v_mfma_f32_16x16x32_bf16 v[38:41], v[168:171], v[208:211], v[38:41]
	v_mfma_f32_16x16x32_bf16 v[34:37], v[180:183], v[208:211], v[34:37]
	v_mfma_f32_16x16x32_bf16 v[22:25], v[168:171], v[216:219], v[22:25]
	v_mfma_f32_16x16x32_bf16 v[18:21], v[180:183], v[216:219], v[18:21]
	v_mfma_f32_16x16x32_bf16 v[6:9], v[168:171], v[224:227], v[6:9]
	v_mfma_f32_16x16x32_bf16 v[2:5], v[180:183], v[224:227], v[2:5]
	v_mfma_f32_16x16x32_bf16 v[54:57], v[172:175], v[204:207], v[54:57]
	v_mfma_f32_16x16x32_bf16 v[50:53], v[184:187], v[204:207], v[50:53]
	v_mfma_f32_16x16x32_bf16 v[38:41], v[172:175], v[212:215], v[38:41]
	v_mfma_f32_16x16x32_bf16 v[34:37], v[184:187], v[212:215], v[34:37]
	v_mfma_f32_16x16x32_bf16 v[22:25], v[172:175], v[220:223], v[22:25]
	v_mfma_f32_16x16x32_bf16 v[18:21], v[184:187], v[220:223], v[18:21]
	v_mfma_f32_16x16x32_bf16 v[6:9], v[172:175], v[228:231], v[6:9]
	v_mfma_f32_16x16x32_bf16 v[2:5], v[184:187], v[228:231], v[2:5]
	s_barrier
	s_setprio 0
	s_add_i32 s62, s62, 2
	s_add_u32 s41, s41, 0x100
	s_addc_u32 s61, s61, 0
	s_cmp_gt_u32 s62, 17
	s_mov_b64 s[20:21], s[24:25]
	s_cbranch_scc0 .LBB0_684
	s_and_b64 vcc, exec, s[16:17]
	s_cbranch_vccz .LBB0_687
	s_barrier

; #define PG8_STAGE(bufoff, gbase, voff) do { _Pragma("unroll") for (int _i = 0; _i < 2; ++_i) \
;         __builtin_amdgcn_global_load_lds((const unsigned*)((const char*)(gbase) + (voff)[_i]), (PG8_LAS unsigned*)(lds + (bufoff) + ldsw + _i * 8192), 16, 0, 0); } while (0)
; #define PG8_LDA(dst, b, h) do { _Pragma("unroll") for (int m = 0; m < 4; ++m) _Pragma("unroll") for (int k = 0; k < 2; ++k) dst[m][k] = *(const PG8_LAS bf16x8*)(lds + PG8_SA(b, h) + aoff + m * 2048 + k * 1024); } while (0)
; #define PG8_LDB(dst, b, h) do { _Pragma("unroll") for (int n = 0; n < 2; ++n) _Pragma("unroll") for (int k = 0; k < 2; ++k) dst[n][k] = *(const PG8_LAS bf16x8*)(lds + PG8_SB(b, h) + boff + n * 2048 + k * 1024); } while (0)
; #define PG8_MMA(ai, bj, At, Bt) do { __builtin_amdgcn_s_setprio(1); _Pragma("unroll") for (int m = 0; m < 4; ++m) _Pragma("unroll") for (int n = 0; n < 2; ++n) _Pragma("unroll") for (int k = 0; k < 2; ++k) \
;         acc[ai][bj][m][n] = __builtin_amdgcn_mfma_f32_16x16x32_bf16(Bt[n][k], At[m][k], acc[ai][bj][m][n], 0, 0, 0); __builtin_amdgcn_s_setprio(0); } while (0)
; #define PG8_WAIT_V(n) asm volatile("s_waitcnt vmcnt(" #n ")" ::: "memory")
; #define PG8_WAIT_L(n) asm volatile("s_waitcnt lgkmcnt(" #n ")" ::: "memory")
; #define PG8_BAR __builtin_amdgcn_s_barrier()
; #define PG8_SCHED __builtin_amdgcn_sched_barrier(0)
; template <class Epi, class Sched, bool ALIGN_EPI = false, bool SP2 = false>
; __device__ __forceinline__ void gemm_phase(PG8_LAS unsigned char* lds, const Gemm g, const Sched& S, const Epi& E) {
;     ...
;             const bool last = (t == nt - 2);
;             const char* a1 = cA + (size_t)(t + 1) * kstep;
;             const char* a2 = last ? nA : cA + (size_t)(t + 2) * kstep; const char* b2 = last ? nB : cB + (size_t)(t + 2) * kstep;
;             const char* a3 = a2 + kstep; const char* b3 = b2 + kstep;
;             if (last && has_next) S.a_ready(nxt);
;             if constexpr (SP2) {
;             PG8_LDB(B0, 0, 0); PG8_LDB(B1, 0, 1); PG8_SCHED; PG8_LDA(At, 0, 0); PG8_STAGE(PG8_SA(1, 1), a1 + hstep, voffA);
;             PG8_WAIT_V(8); PG8_WAIT_L(0); PG8_BAR; PG8_MMA(0, 0, At, B0); PG8_MMA(0, 1, At, B1); PG8_BAR; PG8_SCHED;
;             PG8_LDA(At, 0, 1); PG8_STAGE(PG8_SB(0, 0), b2, voffB); PG8_STAGE(PG8_SB(0, 1), b2 + hstep, voffB); PG8_STAGE(PG8_SA(0, 0), a2, voffA);
.LBB0_700:
	s_add_u32 s59, s60, 0xfffe0080
	s_addc_u32 s62, s61, -1
	s_add_i32 s66, 0, 0x10000
	s_cmp_eq_u32 s56, 4
	s_cselect_b32 s65, s19, s62
	s_cselect_b32 s64, s23, s59
	v_add_u32_e32 v154, s66, v156
	s_cselect_b32 s63, s17, s41
	s_cselect_b32 s62, s27, s40
	s_add_i32 s59, 0, 0x14000
	ds_read_b128 v[146:149], v154
	ds_read_b128 v[150:153], v154 offset:1024
	ds_read_b128 v[160:163], v154 offset:2048
	ds_read_b128 v[164:167], v154 offset:3072
	v_add_u32_e32 v154, s59, v156
	ds_read_b128 v[168:171], v154
	ds_read_b128 v[172:175], v154 offset:1024
	ds_read_b128 v[180:183], v154 offset:2048
	ds_read_b128 v[184:187], v154 offset:3072
	v_lshl_add_u64 v[154:155], s[60:61], 0, v[144:145]
	s_add_i32 m0, s42, 0xc000
	ds_read_b128 v[200:203], v158
	ds_read_b128 v[204:207], v158 offset:1024
	ds_read_b128 v[208:211], v158 offset:2048
	ds_read_b128 v[212:215], v158 offset:3072
	ds_read_b128 v[216:219], v158 offset:4096
	ds_read_b128 v[220:223], v158 offset:5120
	ds_read_b128 v[224:227], v158 offset:6144
	ds_read_b128 v[228:231], v158 offset:7168
	global_load_lds_dwordx4 v[154:155], off
	v_lshl_add_u64 v[154:155], s[60:61], 0, v[142:143]
	s_add_i32 m0, s42, 0xe000
	s_nop 0
	global_load_lds_dwordx4 v[154:155], off
	s_waitcnt vmcnt(8)
	s_waitcnt lgkmcnt(0)
	s_setprio 1
	s_barrier
	v_mfma_f32_16x16x32_bf16 v[130:133], v[146:149], v[200:203], v[130:133]
	v_mfma_f32_16x16x32_bf16 v[126:129], v[160:163], v[200:203], v[126:129]
	v_mfma_f32_16x16x32_bf16 v[114:117], v[146:149], v[208:211], v[114:117]
	v_mfma_f32_16x16x32_bf16 v[110:113], v[160:163], v[208:211], v[110:113]
	v_mfma_f32_16x16x32_bf16 v[98:101], v[146:149], v[216:219], v[98:101]
	v_mfma_f32_16x16x32_bf16 v[94:97], v[160:163], v[216:219], v[94:97]
	v_mfma_f32_16x16x32_bf16 v[78:81], v[146:149], v[224:227], v[78:81]
	v_mfma_f32_16x16x32_bf16 v[74:77], v[160:163], v[224:227], v[74:77]
	v_mfma_f32_16x16x32_bf16 v[130:133], v[150:153], v[204:207], v[130:133]
	v_mfma_f32_16x16x32_bf16 v[126:129], v[164:167], v[204:207], v[126:129]
	v_mfma_f32_16x16x32_bf16 v[114:117], v[150:153], v[212:215], v[114:117]
	v_mfma_f32_16x16x32_bf16 v[110:113], v[164:167], v[212:215], v[110:113]
	v_mfma_f32_16x16x32_bf16 v[98:101], v[150:153], v[220:223], v[98:101]
	v_mfma_f32_16x16x32_bf16 v[94:97], v[164:167], v[220:223], v[94:97]
	v_mfma_f32_16x16x32_bf16 v[78:81], v[150:153], v[228:231], v[78:81]
	v_mfma_f32_16x16x32_bf16 v[74:77], v[164:167], v[228:231], v[74:77]
	v_mfma_f32_16x16x32_bf16 v[122:125], v[168:171], v[200:203], v[122:125]
	v_mfma_f32_16x16x32_bf16 v[118:121], v[180:183], v[200:203], v[118:121]
	v_mfma_f32_16x16x32_bf16 v[106:109], v[168:171], v[208:211], v[106:109]
	v_mfma_f32_16x16x32_bf16 v[102:105], v[180:183], v[208:211], v[102:105]
	v_mfma_f32_16x16x32_bf16 v[90:93], v[168:171], v[216:219], v[90:93]
	v_mfma_f32_16x16x32_bf16 v[86:89], v[180:183], v[216:219], v[86:89]
	v_mfma_f32_16x16x32_bf16 v[70:73], v[168:171], v[224:227], v[70:73]
	v_mfma_f32_16x16x32_bf16 v[66:69], v[180:183], v[224:227], v[66:69]
	v_mfma_f32_16x16x32_bf16 v[122:125], v[172:175], v[204:207], v[122:125]
	v_mfma_f32_16x16x32_bf16 v[118:121], v[184:187], v[204:207], v[118:121]
	v_mfma_f32_16x16x32_bf16 v[106:109], v[172:175], v[212:215], v[106:109]
	v_mfma_f32_16x16x32_bf16 v[102:105], v[184:187], v[212:215], v[102:105]
	v_mfma_f32_16x16x32_bf16 v[90:93], v[172:175], v[220:223], v[90:93]
	v_mfma_f32_16x16x32_bf16 v[86:89], v[184:187], v[220:223], v[86:89]
	v_mfma_f32_16x16x32_bf16 v[70:73], v[172:175], v[228:231], v[70:73]
	v_mfma_f32_16x16x32_bf16 v[66:69], v[184:187], v[228:231], v[66:69]
	s_barrier
	s_setprio 0
	s_add_i32 s66, s66, s29
	v_lshl_add_u64 v[154:155], s[62:63], 0, v[138:139]
	s_mov_b32 m0, s66
	ds_read_b128 v[200:203], v158 offset:16384
	ds_read_b128 v[204:207], v158 offset:17408
	ds_read_b128 v[208:211], v158 offset:18432
	ds_read_b128 v[212:215], v158 offset:19456
	ds_read_b128 v[216:219], v158 offset:20480
	ds_read_b128 v[220:223], v158 offset:21504
	ds_read_b128 v[224:227], v158 offset:22528
	ds_read_b128 v[228:231], v158 offset:23552
	global_load_lds_dwordx4 v[154:155], off
	s_add_i32 m0, s66, 0x2000
	s_add_u32 s66, s62, 0x20000
	v_lshl_add_u64 v[176:177], s[62:63], 0, v[134:135]
	s_addc_u32 s67, s63, 0
	s_add_i32 s59, s59, s29
	global_load_lds_dwordx4 v[176:177], off
	v_lshl_add_u64 v[232:233], s[66:67], 0, v[138:139]
	s_mov_b32 m0, s59
	v_lshl_add_u64 v[234:235], s[64:65], 0, v[136:137]
	global_load_lds_dwordx4 v[232:233], off
	v_lshl_add_u64 v[232:233], s[66:67], 0, v[134:135]
	s_add_i32 m0, s59, 0x2000
	s_nop 0
	global_load_lds_dwordx4 v[232:233], off
	v_lshl_add_u64 v[232:233], s[64:65], 0, v[140:141]
	s_mov_b32 m0, s42
	s_nop 0
	global_load_lds_dwordx4 v[232:233], off
	s_mov_b32 m0, s48
	s_nop 0
	global_load_lds_dwordx4 v[234:235], off
	s_waitcnt vmcnt(8)
	s_waitcnt lgkmcnt(0)
	s_setprio 1
	s_barrier
; #define PG8_STAGE(bufoff, gbase, voff) do { _Pragma("unroll") for (int _i = 0; _i < 2; ++_i) \
;         __builtin_amdgcn_global_load_lds((const unsigned*)((const char*)(gbase) + (voff)[_i]), (PG8_LAS unsigned*)(lds + (bufoff) + ldsw + _i * 8192), 16, 0, 0); } while (0)
; #define PG8_LDA(dst, b, h) do { _Pragma("unroll") for (int m = 0; m < 4; ++m) _Pragma("unroll") for (int k = 0; k < 2; ++k) dst[m][k] = *(const PG8_LAS bf16x8*)(lds + PG8_SA(b, h) + aoff + m * 2048 + k * 1024); } while (0)
; #define PG8_LDB(dst, b, h) do { _Pragma("unroll") for (int n = 0; n < 2; ++n) _Pragma("unroll") for (int k = 0; k < 2; ++k) dst[n][k] = *(const PG8_LAS bf16x8*)(lds + PG8_SB(b, h) + boff + n * 2048 + k * 1024); } while (0)
; #define PG8_MMA(ai, bj, At, Bt) do { __builtin_amdgcn_s_setprio(1); _Pragma("unroll") for (int m = 0; m < 4; ++m) _Pragma("unroll") for (int n = 0; n < 2; ++n) _Pragma("unroll") for (int k = 0; k < 2; ++k) \
;         acc[ai][bj][m][n] = __builtin_amdgcn_mfma_f32_16x16x32_bf16(Bt[n][k], At[m][k], acc[ai][bj][m][n], 0, 0, 0); __builtin_amdgcn_s_setprio(0); } while (0)
; #define PG8_WAIT_V(n) asm volatile("s_waitcnt vmcnt(" #n ")" ::: "memory")
; #define PG8_WAIT_L(n) asm volatile("s_waitcnt lgkmcnt(" #n ")" ::: "memory")
; #define PG8_BAR __builtin_amdgcn_s_barrier()
; #define PG8_SCHED __builtin_amdgcn_sched_barrier(0)
; template <class Epi, class Sched, bool ALIGN_EPI = false, bool SP2 = false>
; __device__ __forceinline__ void gemm_phase(PG8_LAS unsigned char* lds, const Gemm g, const Sched& S, const Epi& E) {
;     ...
;             PG8_WAIT_V(8); PG8_WAIT_L(0); PG8_BAR; PG8_MMA(1, 0, At, B0); PG8_MMA(1, 1, At, B1); PG8_BAR; PG8_SCHED;
;             PG8_LDB(B0, 1, 0); PG8_LDB(B1, 1, 1); PG8_SCHED; PG8_LDA(At, 1, 0); PG8_STAGE(PG8_SA(0, 1), a2 + hstep, voffA);
;             PG8_WAIT_V(8); PG8_WAIT_L(0); PG8_BAR; PG8_MMA(0, 0, At, B0); PG8_MMA(0, 1, At, B1); PG8_BAR; PG8_SCHED;
	v_mfma_f32_16x16x32_bf16 v[62:65], v[146:149], v[200:203], v[62:65]
	v_mfma_f32_16x16x32_bf16 v[58:61], v[160:163], v[200:203], v[58:61]
	v_mfma_f32_16x16x32_bf16 v[46:49], v[146:149], v[208:211], v[46:49]
	v_mfma_f32_16x16x32_bf16 v[42:45], v[160:163], v[208:211], v[42:45]
	v_mfma_f32_16x16x32_bf16 v[30:33], v[146:149], v[216:219], v[30:33]
	v_mfma_f32_16x16x32_bf16 v[26:29], v[160:163], v[216:219], v[26:29]
	v_mfma_f32_16x16x32_bf16 v[14:17], v[146:149], v[224:227], v[14:17]
	v_mfma_f32_16x16x32_bf16 v[10:13], v[160:163], v[224:227], v[10:13]
	v_mfma_f32_16x16x32_bf16 v[62:65], v[150:153], v[204:207], v[62:65]
	v_mfma_f32_16x16x32_bf16 v[58:61], v[164:167], v[204:207], v[58:61]
	v_mfma_f32_16x16x32_bf16 v[46:49], v[150:153], v[212:215], v[46:49]
	v_mfma_f32_16x16x32_bf16 v[42:45], v[164:167], v[212:215], v[42:45]
	v_mfma_f32_16x16x32_bf16 v[30:33], v[150:153], v[220:223], v[30:33]
	v_mfma_f32_16x16x32_bf16 v[26:29], v[164:167], v[220:223], v[26:29]
	v_mfma_f32_16x16x32_bf16 v[14:17], v[150:153], v[228:231], v[14:17]
	v_mfma_f32_16x16x32_bf16 v[10:13], v[164:167], v[228:231], v[10:13]
	v_mfma_f32_16x16x32_bf16 v[54:57], v[168:171], v[200:203], v[54:57]
	v_mfma_f32_16x16x32_bf16 v[50:53], v[180:183], v[200:203], v[50:53]
	v_mfma_f32_16x16x32_bf16 v[38:41], v[168:171], v[208:211], v[38:41]
	v_mfma_f32_16x16x32_bf16 v[34:37], v[180:183], v[208:211], v[34:37]
	v_mfma_f32_16x16x32_bf16 v[22:25], v[168:171], v[216:219], v[22:25]
	v_mfma_f32_16x16x32_bf16 v[18:21], v[180:183], v[216:219], v[18:21]
	v_mfma_f32_16x16x32_bf16 v[6:9], v[168:171], v[224:227], v[6:9]
	v_mfma_f32_16x16x32_bf16 v[2:5], v[180:183], v[224:227], v[2:5]
	v_mfma_f32_16x16x32_bf16 v[54:57], v[172:175], v[204:207], v[54:57]
	v_mfma_f32_16x16x32_bf16 v[50:53], v[184:187], v[204:207], v[50:53]
	v_mfma_f32_16x16x32_bf16 v[38:41], v[172:175], v[212:215], v[38:41]
	v_mfma_f32_16x16x32_bf16 v[34:37], v[184:187], v[212:215], v[34:37]
	v_mfma_f32_16x16x32_bf16 v[22:25], v[172:175], v[220:223], v[22:25]
	v_mfma_f32_16x16x32_bf16 v[18:21], v[184:187], v[220:223], v[18:21]
	v_mfma_f32_16x16x32_bf16 v[6:9], v[172:175], v[228:231], v[6:9]
	v_mfma_f32_16x16x32_bf16 v[2:5], v[184:187], v[228:231], v[2:5]
	s_barrier
	s_setprio 0
	s_add_i32 s59, 0, 0x18000
	v_add_u32_e32 v159, s59, v156
	s_add_i32 s66, 0, 0x1c000
	ds_read_b128 v[146:149], v159
	ds_read_b128 v[150:153], v159 offset:1024
	ds_read_b128 v[160:163], v159 offset:2048
	ds_read_b128 v[164:167], v159 offset:3072
	v_add_u32_e32 v159, s66, v156
	ds_read_b128 v[168:171], v159
	ds_read_b128 v[172:175], v159 offset:1024
	ds_read_b128 v[180:183], v159 offset:2048
	ds_read_b128 v[184:187], v159 offset:3072
	s_add_u32 s64, s64, 0x20000
	s_addc_u32 s65, s65, 0
	s_mov_b32 m0, s49
	v_lshl_add_u64 v[236:237], s[64:65], 0, v[140:141]
	ds_read_b128 v[200:203], v158 offset:32768
	ds_read_b128 v[204:207], v158 offset:33792
	ds_read_b128 v[208:211], v158 offset:34816
	ds_read_b128 v[212:215], v158 offset:35840
	ds_read_b128 v[216:219], v158 offset:36864
	ds_read_b128 v[220:223], v158 offset:37888
	ds_read_b128 v[224:227], v158 offset:38912
	ds_read_b128 v[228:231], v158 offset:39936
	global_load_lds_dwordx4 v[236:237], off
	v_lshl_add_u64 v[236:237], s[64:65], 0, v[136:137]
	s_mov_b32 m0, s52
	s_nop 0
	global_load_lds_dwordx4 v[236:237], off
	s_waitcnt vmcnt(8)
	s_waitcnt lgkmcnt(0)
	s_setprio 1
	s_barrier
	v_mfma_f32_16x16x32_bf16 v[130:133], v[146:149], v[200:203], v[130:133]
	v_mfma_f32_16x16x32_bf16 v[126:129], v[160:163], v[200:203], v[126:129]
	v_mfma_f32_16x16x32_bf16 v[114:117], v[146:149], v[208:211], v[114:117]
	v_mfma_f32_16x16x32_bf16 v[110:113], v[160:163], v[208:211], v[110:113]
	v_mfma_f32_16x16x32_bf16 v[98:101], v[146:149], v[216:219], v[98:101]
	v_mfma_f32_16x16x32_bf16 v[94:97], v[160:163], v[216:219], v[94:97]
	v_mfma_f32_16x16x32_bf16 v[78:81], v[146:149], v[224:227], v[78:81]
	v_mfma_f32_16x16x32_bf16 v[74:77], v[160:163], v[224:227], v[74:77]
	v_mfma_f32_16x16x32_bf16 v[130:133], v[150:153], v[204:207], v[130:133]
	v_mfma_f32_16x16x32_bf16 v[126:129], v[164:167], v[204:207], v[126:129]
	v_mfma_f32_16x16x32_bf16 v[114:117], v[150:153], v[212:215], v[114:117]
	v_mfma_f32_16x16x32_bf16 v[110:113], v[164:167], v[212:215], v[110:113]
	v_mfma_f32_16x16x32_bf16 v[98:101], v[150:153], v[220:223], v[98:101]
	v_mfma_f32_16x16x32_bf16 v[94:97], v[164:167], v[220:223], v[94:97]
	v_mfma_f32_16x16x32_bf16 v[78:81], v[150:153], v[228:231], v[78:81]
	v_mfma_f32_16x16x32_bf16 v[74:77], v[164:167], v[228:231], v[74:77]
	v_mfma_f32_16x16x32_bf16 v[122:125], v[168:171], v[200:203], v[122:125]
	v_mfma_f32_16x16x32_bf16 v[118:121], v[180:183], v[200:203], v[118:121]
	v_mfma_f32_16x16x32_bf16 v[106:109], v[168:171], v[208:211], v[106:109]
	v_mfma_f32_16x16x32_bf16 v[102:105], v[180:183], v[208:211], v[102:105]
	v_mfma_f32_16x16x32_bf16 v[90:93], v[168:171], v[216:219], v[90:93]
	v_mfma_f32_16x16x32_bf16 v[86:89], v[180:183], v[216:219], v[86:89]
	v_mfma_f32_16x16x32_bf16 v[70:73], v[168:171], v[224:227], v[70:73]
	v_mfma_f32_16x16x32_bf16 v[66:69], v[180:183], v[224:227], v[66:69]
	v_mfma_f32_16x16x32_bf16 v[122:125], v[172:175], v[204:207], v[122:125]
	v_mfma_f32_16x16x32_bf16 v[118:121], v[184:187], v[204:207], v[118:121]
	v_mfma_f32_16x16x32_bf16 v[106:109], v[172:175], v[212:215], v[106:109]
	v_mfma_f32_16x16x32_bf16 v[102:105], v[184:187], v[212:215], v[102:105]
	v_mfma_f32_16x16x32_bf16 v[90:93], v[172:175], v[220:223], v[90:93]
	v_mfma_f32_16x16x32_bf16 v[86:89], v[184:187], v[220:223], v[86:89]
	v_mfma_f32_16x16x32_bf16 v[70:73], v[172:175], v[228:231], v[70:73]
	v_mfma_f32_16x16x32_bf16 v[66:69], v[184:187], v[228:231], v[66:69]
	s_barrier
; #define PG8_STAGE(bufoff, gbase, voff) do { _Pragma("unroll") for (int _i = 0; _i < 2; ++_i) \
;         __builtin_amdgcn_global_load_lds((const unsigned*)((const char*)(gbase) + (voff)[_i]), (PG8_LAS unsigned*)(lds + (bufoff) + ldsw + _i * 8192), 16, 0, 0); } while (0)
; #define PG8_LDA(dst, b, h) do { _Pragma("unroll") for (int m = 0; m < 4; ++m) _Pragma("unroll") for (int k = 0; k < 2; ++k) dst[m][k] = *(const PG8_LAS bf16x8*)(lds + PG8_SA(b, h) + aoff + m * 2048 + k * 1024); } while (0)
; #define PG8_MMA(ai, bj, At, Bt) do { __builtin_amdgcn_s_setprio(1); _Pragma("unroll") for (int m = 0; m < 4; ++m) _Pragma("unroll") for (int n = 0; n < 2; ++n) _Pragma("unroll") for (int k = 0; k < 2; ++k) \
;         acc[ai][bj][m][n] = __builtin_amdgcn_mfma_f32_16x16x32_bf16(Bt[n][k], At[m][k], acc[ai][bj][m][n], 0, 0, 0); __builtin_amdgcn_s_setprio(0); } while (0)
; #define PG8_WAIT_V(n) asm volatile("s_waitcnt vmcnt(" #n ")" ::: "memory")
; #define PG8_WAIT_L(n) asm volatile("s_waitcnt lgkmcnt(" #n ")" ::: "memory")
; #define PG8_BAR __builtin_amdgcn_s_barrier()
; #define PG8_SCHED __builtin_amdgcn_sched_barrier(0)
; template <class Epi, class Sched, bool ALIGN_EPI = false, bool SP2 = false>
; __device__ __forceinline__ void gemm_phase(PG8_LAS unsigned char* lds, const Gemm g, const Sched& S, const Epi& E) {
;     ...
;         for (int t = 0; t < nt; t += 2) {
;             const bool last = (t == nt - 2);
;             const char* a1 = cA + (size_t)(t + 1) * kstep;
;             const char* a2 = last ? nA : cA + (size_t)(t + 2) * kstep; const char* b2 = last ? nB : cB + (size_t)(t + 2) * kstep;
;     ...
;             PG8_LDA(At, 1, 1); PG8_STAGE(PG8_SB(1, 0), b3, voffB); PG8_STAGE(PG8_SB(1, 1), b3 + hstep, voffB); PG8_STAGE(PG8_SA(1, 0), a3, voffA);
;             PG8_WAIT_V(8); PG8_WAIT_L(0); PG8_BAR; PG8_MMA(1, 0, At, B0); PG8_MMA(1, 1, At, B1); PG8_BAR; PG8_SCHED;
	s_setprio 0
	s_add_i32 s59, s59, s29
	v_lshl_add_u64 v[154:155], v[154:155], 0, s[38:39]
	s_mov_b32 m0, s59
	ds_read_b128 v[200:203], v158 offset:49152
	ds_read_b128 v[204:207], v158 offset:50176
	ds_read_b128 v[208:211], v158 offset:51200
	ds_read_b128 v[212:215], v158 offset:52224
	ds_read_b128 v[216:219], v158 offset:53248
	ds_read_b128 v[220:223], v158 offset:54272
	ds_read_b128 v[224:227], v158 offset:55296
	ds_read_b128 v[228:231], v158 offset:56320
	global_load_lds_dwordx4 v[154:155], off
	s_add_i32 m0, s59, 0x2000
	s_add_u32 s62, s62, 0x20080
	v_lshl_add_u64 v[154:155], v[176:177], 0, s[38:39]
	s_addc_u32 s63, s63, 0
	s_add_i32 s59, s66, s29
	global_load_lds_dwordx4 v[154:155], off
	v_lshl_add_u64 v[154:155], s[62:63], 0, v[138:139]
	s_mov_b32 m0, s59
	s_nop 0
	global_load_lds_dwordx4 v[154:155], off
	v_lshl_add_u64 v[154:155], s[62:63], 0, v[134:135]
	s_add_i32 m0, s59, 0x2000
	s_nop 0
	global_load_lds_dwordx4 v[154:155], off
	v_lshl_add_u64 v[154:155], v[232:233], 0, s[38:39]
	s_mov_b32 m0, s53
	s_nop 0
	global_load_lds_dwordx4 v[154:155], off
	v_lshl_add_u64 v[154:155], v[234:235], 0, s[38:39]
	s_mov_b32 m0, s54
	s_nop 0
	global_load_lds_dwordx4 v[154:155], off
	s_waitcnt vmcnt(8)
	s_waitcnt lgkmcnt(0)
	s_setprio 1
	s_barrier
	v_mfma_f32_16x16x32_bf16 v[62:65], v[146:149], v[200:203], v[62:65]
	v_mfma_f32_16x16x32_bf16 v[58:61], v[160:163], v[200:203], v[58:61]
	v_mfma_f32_16x16x32_bf16 v[46:49], v[146:149], v[208:211], v[46:49]
	v_mfma_f32_16x16x32_bf16 v[42:45], v[160:163], v[208:211], v[42:45]
	v_mfma_f32_16x16x32_bf16 v[30:33], v[146:149], v[216:219], v[30:33]
	v_mfma_f32_16x16x32_bf16 v[26:29], v[160:163], v[216:219], v[26:29]
	v_mfma_f32_16x16x32_bf16 v[14:17], v[146:149], v[224:227], v[14:17]
	v_mfma_f32_16x16x32_bf16 v[10:13], v[160:163], v[224:227], v[10:13]
	v_mfma_f32_16x16x32_bf16 v[62:65], v[150:153], v[204:207], v[62:65]
	v_mfma_f32_16x16x32_bf16 v[58:61], v[164:167], v[204:207], v[58:61]
	v_mfma_f32_16x16x32_bf16 v[46:49], v[150:153], v[212:215], v[46:49]
	v_mfma_f32_16x16x32_bf16 v[42:45], v[164:167], v[212:215], v[42:45]
	v_mfma_f32_16x16x32_bf16 v[30:33], v[150:153], v[220:223], v[30:33]
	v_mfma_f32_16x16x32_bf16 v[26:29], v[164:167], v[220:223], v[26:29]
	v_mfma_f32_16x16x32_bf16 v[14:17], v[150:153], v[228:231], v[14:17]
	v_mfma_f32_16x16x32_bf16 v[10:13], v[164:167], v[228:231], v[10:13]
	v_mfma_f32_16x16x32_bf16 v[54:57], v[168:171], v[200:203], v[54:57]
	v_mfma_f32_16x16x32_bf16 v[50:53], v[180:183], v[200:203], v[50:53]
	v_mfma_f32_16x16x32_bf16 v[38:41], v[168:171], v[208:211], v[38:41]
	v_mfma_f32_16x16x32_bf16 v[34:37], v[180:183], v[208:211], v[34:37]
	v_mfma_f32_16x16x32_bf16 v[22:25], v[168:171], v[216:219], v[22:25]
	v_mfma_f32_16x16x32_bf16 v[18:21], v[180:183], v[216:219], v[18:21]
	v_mfma_f32_16x16x32_bf16 v[6:9], v[168:171], v[224:227], v[6:9]
	v_mfma_f32_16x16x32_bf16 v[2:5], v[180:183], v[224:227], v[2:5]
	v_mfma_f32_16x16x32_bf16 v[54:57], v[172:175], v[204:207], v[54:57]
	v_mfma_f32_16x16x32_bf16 v[50:53], v[184:187], v[204:207], v[50:53]
	v_mfma_f32_16x16x32_bf16 v[38:41], v[172:175], v[212:215], v[38:41]
	v_mfma_f32_16x16x32_bf16 v[34:37], v[184:187], v[212:215], v[34:37]
	v_mfma_f32_16x16x32_bf16 v[22:25], v[172:175], v[220:223], v[22:25]
	v_mfma_f32_16x16x32_bf16 v[18:21], v[184:187], v[220:223], v[18:21]
	v_mfma_f32_16x16x32_bf16 v[6:9], v[172:175], v[228:231], v[6:9]
	v_mfma_f32_16x16x32_bf16 v[2:5], v[184:187], v[228:231], v[2:5]
	s_barrier
	s_setprio 0
	s_add_i32 s56, s56, 2
	s_add_u32 s40, s40, 0x100
	s_addc_u32 s41, s41, 0
	s_add_u32 s60, s60, 0x100
	s_addc_u32 s61, s61, 0
	s_cmp_gt_u32 s56, 5
	s_cbranch_scc0 .LBB0_700
	s_and_b64 vcc, exec, s[14:15]
	s_cbranch_vccz .LBB0_703
	s_barrier

; #define PG8_STAGE(bufoff, gbase, voff) do { _Pragma("unroll") for (int _i = 0; _i < 2; ++_i) \
;         __builtin_amdgcn_global_load_lds((const unsigned*)((const char*)(gbase) + (voff)[_i]), (PG8_LAS unsigned*)(lds + (bufoff) + ldsw + _i * 8192), 16, 0, 0); } while (0)
; #define PG8_LDA(dst, b, h) do { _Pragma("unroll") for (int m = 0; m < 4; ++m) _Pragma("unroll") for (int k = 0; k < 2; ++k) dst[m][k] = *(const PG8_LAS bf16x8*)(lds + PG8_SA(b, h) + aoff + m * 2048 + k * 1024); } while (0)
; #define PG8_LDB(dst, b, h) do { _Pragma("unroll") for (int n = 0; n < 2; ++n) _Pragma("unroll") for (int k = 0; k < 2; ++k) dst[n][k] = *(const PG8_LAS bf16x8*)(lds + PG8_SB(b, h) + boff + n * 2048 + k * 1024); } while (0)
; #define PG8_MMA(ai, bj, At, Bt) do { __builtin_amdgcn_s_setprio(1); _Pragma("unroll") for (int m = 0; m < 4; ++m) _Pragma("unroll") for (int n = 0; n < 2; ++n) _Pragma("unroll") for (int k = 0; k < 2; ++k) \
;         acc[ai][bj][m][n] = __builtin_amdgcn_mfma_f32_16x16x32_bf16(Bt[n][k], At[m][k], acc[ai][bj][m][n], 0, 0, 0); __builtin_amdgcn_s_setprio(0); } while (0)
; #define PG8_WAIT_V(n) asm volatile("s_waitcnt vmcnt(" #n ")" ::: "memory")
; #define PG8_WAIT_L(n) asm volatile("s_waitcnt lgkmcnt(" #n ")" ::: "memory")
; #define PG8_BAR __builtin_amdgcn_s_barrier()
; #define PG8_SCHED __builtin_amdgcn_sched_barrier(0)
; template <class Epi, class Sched, bool ALIGN_EPI = false, bool SP2 = false>
; __device__ __forceinline__ void gemm_phase(PG8_LAS unsigned char* lds, const Gemm g, const Sched& S, const Epi& E) {
;     ...
;             const bool last = (t == nt - 2);
;             const char* a1 = cA + (size_t)(t + 1) * kstep;
;             const char* a2 = last ? nA : cA + (size_t)(t + 2) * kstep; const char* b2 = last ? nB : cB + (size_t)(t + 2) * kstep;
;             const char* a3 = a2 + kstep; const char* b3 = b2 + kstep;
;             if (last && has_next) S.a_ready(nxt);
;             if constexpr (SP2) {
;             PG8_LDB(B0, 0, 0); PG8_LDB(B1, 0, 1); PG8_SCHED; PG8_LDA(At, 0, 0); PG8_STAGE(PG8_SA(1, 1), a1 + hstep, voffA);
;             PG8_WAIT_V(8); PG8_WAIT_L(0); PG8_BAR; PG8_MMA(0, 0, At, B0); PG8_MMA(0, 1, At, B1); PG8_BAR; PG8_SCHED;
;             PG8_LDA(At, 0, 1); PG8_STAGE(PG8_SB(0, 0), b2, voffB); PG8_STAGE(PG8_SB(0, 1), b2 + hstep, voffB); PG8_STAGE(PG8_SA(0, 0), a2, voffA);
.LBB0_770:
	s_add_u32 s65, s66, 0xfffc0080
	s_addc_u32 s68, s67, -1
	s_add_i32 s72, 0, 0x10000
	s_cmp_eq_u32 s63, 12
	s_cselect_b32 s71, s27, s68
	s_cselect_b32 s70, s53, s65
	v_add_u32_e32 v146, s72, v148
	s_cselect_b32 s69, s25, s56
	s_cselect_b32 s68, s54, s55
	s_add_i32 s65, 0, 0x14000
	ds_read_b128 v[142:145], v146
	ds_read_b128 v[152:155], v146 offset:1024
	ds_read_b128 v[156:159], v146 offset:2048
	ds_read_b128 v[160:163], v146 offset:3072
	v_add_u32_e32 v146, s65, v148
	ds_read_b128 v[164:167], v146
	ds_read_b128 v[168:171], v146 offset:1024
	ds_read_b128 v[172:175], v146 offset:2048
	ds_read_b128 v[180:183], v146 offset:3072
	v_lshl_add_u64 v[146:147], s[66:67], 0, v[140:141]
	s_add_i32 m0, s29, 0xc000
	ds_read_b128 v[184:187], v150
	ds_read_b128 v[200:203], v150 offset:1024
	ds_read_b128 v[204:207], v150 offset:2048
	ds_read_b128 v[208:211], v150 offset:3072
	ds_read_b128 v[212:215], v150 offset:4096
	ds_read_b128 v[216:219], v150 offset:5120
	ds_read_b128 v[220:223], v150 offset:6144
	ds_read_b128 v[224:227], v150 offset:7168
	global_load_lds_dwordx4 v[146:147], off
	v_lshl_add_u64 v[146:147], s[66:67], 0, v[138:139]
	s_add_i32 m0, s29, 0xe000
	s_nop 0
	global_load_lds_dwordx4 v[146:147], off
	s_waitcnt vmcnt(8)
	s_waitcnt lgkmcnt(0)
	s_setprio 1
	s_barrier
	v_mfma_f32_16x16x32_bf16 v[130:133], v[142:145], v[184:187], v[130:133]
	v_mfma_f32_16x16x32_bf16 v[126:129], v[156:159], v[184:187], v[126:129]
	v_mfma_f32_16x16x32_bf16 v[114:117], v[142:145], v[204:207], v[114:117]
	v_mfma_f32_16x16x32_bf16 v[110:113], v[156:159], v[204:207], v[110:113]
	v_mfma_f32_16x16x32_bf16 v[98:101], v[142:145], v[212:215], v[98:101]
	v_mfma_f32_16x16x32_bf16 v[94:97], v[156:159], v[212:215], v[94:97]
	v_mfma_f32_16x16x32_bf16 v[78:81], v[142:145], v[220:223], v[78:81]
	v_mfma_f32_16x16x32_bf16 v[74:77], v[156:159], v[220:223], v[74:77]
	v_mfma_f32_16x16x32_bf16 v[130:133], v[152:155], v[200:203], v[130:133]
	v_mfma_f32_16x16x32_bf16 v[126:129], v[160:163], v[200:203], v[126:129]
	v_mfma_f32_16x16x32_bf16 v[114:117], v[152:155], v[208:211], v[114:117]
	v_mfma_f32_16x16x32_bf16 v[110:113], v[160:163], v[208:211], v[110:113]
	v_mfma_f32_16x16x32_bf16 v[98:101], v[152:155], v[216:219], v[98:101]
	v_mfma_f32_16x16x32_bf16 v[94:97], v[160:163], v[216:219], v[94:97]
	v_mfma_f32_16x16x32_bf16 v[78:81], v[152:155], v[224:227], v[78:81]
	v_mfma_f32_16x16x32_bf16 v[74:77], v[160:163], v[224:227], v[74:77]
	v_mfma_f32_16x16x32_bf16 v[122:125], v[164:167], v[184:187], v[122:125]
	v_mfma_f32_16x16x32_bf16 v[118:121], v[172:175], v[184:187], v[118:121]
	v_mfma_f32_16x16x32_bf16 v[106:109], v[164:167], v[204:207], v[106:109]
	v_mfma_f32_16x16x32_bf16 v[102:105], v[172:175], v[204:207], v[102:105]
	v_mfma_f32_16x16x32_bf16 v[90:93], v[164:167], v[212:215], v[90:93]
	v_mfma_f32_16x16x32_bf16 v[86:89], v[172:175], v[212:215], v[86:89]
	v_mfma_f32_16x16x32_bf16 v[70:73], v[164:167], v[220:223], v[70:73]
	v_mfma_f32_16x16x32_bf16 v[66:69], v[172:175], v[220:223], v[66:69]
	v_mfma_f32_16x16x32_bf16 v[122:125], v[168:171], v[200:203], v[122:125]
	v_mfma_f32_16x16x32_bf16 v[118:121], v[180:183], v[200:203], v[118:121]
	v_mfma_f32_16x16x32_bf16 v[106:109], v[168:171], v[208:211], v[106:109]
	v_mfma_f32_16x16x32_bf16 v[102:105], v[180:183], v[208:211], v[102:105]
	v_mfma_f32_16x16x32_bf16 v[90:93], v[168:171], v[216:219], v[90:93]
	v_mfma_f32_16x16x32_bf16 v[86:89], v[180:183], v[216:219], v[86:89]
	v_mfma_f32_16x16x32_bf16 v[70:73], v[168:171], v[224:227], v[70:73]
	v_mfma_f32_16x16x32_bf16 v[66:69], v[180:183], v[224:227], v[66:69]
	s_barrier
	s_setprio 0
	s_add_i32 s72, s72, s28
	v_lshl_add_u64 v[146:147], s[68:69], 0, v[134:135]
	s_mov_b32 m0, s72
	ds_read_b128 v[184:187], v150 offset:16384
	ds_read_b128 v[200:203], v150 offset:17408
	ds_read_b128 v[204:207], v150 offset:18432
	ds_read_b128 v[208:211], v150 offset:19456
	ds_read_b128 v[212:215], v150 offset:20480
	ds_read_b128 v[216:219], v150 offset:21504
	ds_read_b128 v[220:223], v150 offset:22528
	ds_read_b128 v[224:227], v150 offset:23552
	global_load_lds_dwordx4 v[146:147], off
	s_add_i32 m0, s72, 0x2000
	s_add_u32 s72, s68, 0x40000
	v_lshl_add_u64 v[176:177], s[68:69], 0, v[136:137]
	s_addc_u32 s73, s69, 0
	s_add_i32 s65, s65, s28
	global_load_lds_dwordx4 v[176:177], off
	v_lshl_add_u64 v[228:229], s[72:73], 0, v[134:135]
	s_mov_b32 m0, s65
	v_lshl_add_u64 v[230:231], s[70:71], 0, v[136:137]
	global_load_lds_dwordx4 v[228:229], off
	v_lshl_add_u64 v[228:229], s[72:73], 0, v[136:137]
	s_add_i32 m0, s65, 0x2000
	s_nop 0
	global_load_lds_dwordx4 v[228:229], off
	v_lshl_add_u64 v[228:229], s[70:71], 0, v[134:135]
	s_mov_b32 m0, s29
	s_nop 0
	global_load_lds_dwordx4 v[228:229], off
	s_mov_b32 m0, s34
	s_nop 0
	global_load_lds_dwordx4 v[230:231], off
	s_waitcnt vmcnt(8)
	s_waitcnt lgkmcnt(0)
	s_setprio 1
	s_barrier
; #define PG8_STAGE(bufoff, gbase, voff) do { _Pragma("unroll") for (int _i = 0; _i < 2; ++_i) \
;         __builtin_amdgcn_global_load_lds((const unsigned*)((const char*)(gbase) + (voff)[_i]), (PG8_LAS unsigned*)(lds + (bufoff) + ldsw + _i * 8192), 16, 0, 0); } while (0)
; #define PG8_LDA(dst, b, h) do { _Pragma("unroll") for (int m = 0; m < 4; ++m) _Pragma("unroll") for (int k = 0; k < 2; ++k) dst[m][k] = *(const PG8_LAS bf16x8*)(lds + PG8_SA(b, h) + aoff + m * 2048 + k * 1024); } while (0)
; #define PG8_LDB(dst, b, h) do { _Pragma("unroll") for (int n = 0; n < 2; ++n) _Pragma("unroll") for (int k = 0; k < 2; ++k) dst[n][k] = *(const PG8_LAS bf16x8*)(lds + PG8_SB(b, h) + boff + n * 2048 + k * 1024); } while (0)
; #define PG8_MMA(ai, bj, At, Bt) do { __builtin_amdgcn_s_setprio(1); _Pragma("unroll") for (int m = 0; m < 4; ++m) _Pragma("unroll") for (int n = 0; n < 2; ++n) _Pragma("unroll") for (int k = 0; k < 2; ++k) \
;         acc[ai][bj][m][n] = __builtin_amdgcn_mfma_f32_16x16x32_bf16(Bt[n][k], At[m][k], acc[ai][bj][m][n], 0, 0, 0); __builtin_amdgcn_s_setprio(0); } while (0)
; #define PG8_WAIT_V(n) asm volatile("s_waitcnt vmcnt(" #n ")" ::: "memory")
; #define PG8_WAIT_L(n) asm volatile("s_waitcnt lgkmcnt(" #n ")" ::: "memory")
; #define PG8_BAR __builtin_amdgcn_s_barrier()
; #define PG8_SCHED __builtin_amdgcn_sched_barrier(0)
; template <class Epi, class Sched, bool ALIGN_EPI = false, bool SP2 = false>
; __device__ __forceinline__ void gemm_phase(PG8_LAS unsigned char* lds, const Gemm g, const Sched& S, const Epi& E) {
;     ...
;             PG8_WAIT_V(8); PG8_WAIT_L(0); PG8_BAR; PG8_MMA(1, 0, At, B0); PG8_MMA(1, 1, At, B1); PG8_BAR; PG8_SCHED;
;             PG8_LDB(B0, 1, 0); PG8_LDB(B1, 1, 1); PG8_SCHED; PG8_LDA(At, 1, 0); PG8_STAGE(PG8_SA(0, 1), a2 + hstep, voffA);
;             PG8_WAIT_V(8); PG8_WAIT_L(0); PG8_BAR; PG8_MMA(0, 0, At, B0); PG8_MMA(0, 1, At, B1); PG8_BAR; PG8_SCHED;
	v_mfma_f32_16x16x32_bf16 v[62:65], v[142:145], v[184:187], v[62:65]
	v_mfma_f32_16x16x32_bf16 v[58:61], v[156:159], v[184:187], v[58:61]
	v_mfma_f32_16x16x32_bf16 v[46:49], v[142:145], v[204:207], v[46:49]
	v_mfma_f32_16x16x32_bf16 v[42:45], v[156:159], v[204:207], v[42:45]
	v_mfma_f32_16x16x32_bf16 v[30:33], v[142:145], v[212:215], v[30:33]
	v_mfma_f32_16x16x32_bf16 v[26:29], v[156:159], v[212:215], v[26:29]
	v_mfma_f32_16x16x32_bf16 v[14:17], v[142:145], v[220:223], v[14:17]
	v_mfma_f32_16x16x32_bf16 v[10:13], v[156:159], v[220:223], v[10:13]
	v_mfma_f32_16x16x32_bf16 v[62:65], v[152:155], v[200:203], v[62:65]
	v_mfma_f32_16x16x32_bf16 v[58:61], v[160:163], v[200:203], v[58:61]
	v_mfma_f32_16x16x32_bf16 v[46:49], v[152:155], v[208:211], v[46:49]
	v_mfma_f32_16x16x32_bf16 v[42:45], v[160:163], v[208:211], v[42:45]
	v_mfma_f32_16x16x32_bf16 v[30:33], v[152:155], v[216:219], v[30:33]
	v_mfma_f32_16x16x32_bf16 v[26:29], v[160:163], v[216:219], v[26:29]
	v_mfma_f32_16x16x32_bf16 v[14:17], v[152:155], v[224:227], v[14:17]
	v_mfma_f32_16x16x32_bf16 v[10:13], v[160:163], v[224:227], v[10:13]
	v_mfma_f32_16x16x32_bf16 v[54:57], v[164:167], v[184:187], v[54:57]
	v_mfma_f32_16x16x32_bf16 v[50:53], v[172:175], v[184:187], v[50:53]
	v_mfma_f32_16x16x32_bf16 v[38:41], v[164:167], v[204:207], v[38:41]
	v_mfma_f32_16x16x32_bf16 v[34:37], v[172:175], v[204:207], v[34:37]
	v_mfma_f32_16x16x32_bf16 v[22:25], v[164:167], v[212:215], v[22:25]
	v_mfma_f32_16x16x32_bf16 v[18:21], v[172:175], v[212:215], v[18:21]
	v_mfma_f32_16x16x32_bf16 v[6:9], v[164:167], v[220:223], v[6:9]
	v_mfma_f32_16x16x32_bf16 v[2:5], v[172:175], v[220:223], v[2:5]
	v_mfma_f32_16x16x32_bf16 v[54:57], v[168:171], v[200:203], v[54:57]
	v_mfma_f32_16x16x32_bf16 v[50:53], v[180:183], v[200:203], v[50:53]
	v_mfma_f32_16x16x32_bf16 v[38:41], v[168:171], v[208:211], v[38:41]
	v_mfma_f32_16x16x32_bf16 v[34:37], v[180:183], v[208:211], v[34:37]
	v_mfma_f32_16x16x32_bf16 v[22:25], v[168:171], v[216:219], v[22:25]
	v_mfma_f32_16x16x32_bf16 v[18:21], v[180:183], v[216:219], v[18:21]
	v_mfma_f32_16x16x32_bf16 v[6:9], v[168:171], v[224:227], v[6:9]
	v_mfma_f32_16x16x32_bf16 v[2:5], v[180:183], v[224:227], v[2:5]
	s_barrier
	s_setprio 0
	s_add_i32 s65, 0, 0x18000
	v_add_u32_e32 v151, s65, v148
	s_add_i32 s72, 0, 0x1c000
	ds_read_b128 v[142:145], v151
	ds_read_b128 v[152:155], v151 offset:1024
	ds_read_b128 v[156:159], v151 offset:2048
	ds_read_b128 v[160:163], v151 offset:3072
	v_add_u32_e32 v151, s72, v148
	ds_read_b128 v[164:167], v151
	ds_read_b128 v[168:171], v151 offset:1024
	ds_read_b128 v[172:175], v151 offset:2048
	ds_read_b128 v[180:183], v151 offset:3072
	s_add_u32 s70, s70, 0x40000
	s_addc_u32 s71, s71, 0
	s_mov_b32 m0, s36
	v_lshl_add_u64 v[232:233], s[70:71], 0, v[134:135]
	ds_read_b128 v[184:187], v150 offset:32768
	ds_read_b128 v[200:203], v150 offset:33792
	ds_read_b128 v[204:207], v150 offset:34816
	ds_read_b128 v[208:211], v150 offset:35840
	ds_read_b128 v[212:215], v150 offset:36864
	ds_read_b128 v[216:219], v150 offset:37888
	ds_read_b128 v[220:223], v150 offset:38912
	ds_read_b128 v[224:227], v150 offset:39936
	global_load_lds_dwordx4 v[232:233], off
	v_lshl_add_u64 v[232:233], s[70:71], 0, v[136:137]
	s_mov_b32 m0, s37
	s_nop 0
	global_load_lds_dwordx4 v[232:233], off
	s_waitcnt vmcnt(8)
	s_waitcnt lgkmcnt(0)
	s_setprio 1
	s_barrier
	v_mfma_f32_16x16x32_bf16 v[130:133], v[142:145], v[184:187], v[130:133]
	v_mfma_f32_16x16x32_bf16 v[126:129], v[156:159], v[184:187], v[126:129]
	v_mfma_f32_16x16x32_bf16 v[114:117], v[142:145], v[204:207], v[114:117]
	v_mfma_f32_16x16x32_bf16 v[110:113], v[156:159], v[204:207], v[110:113]
	v_mfma_f32_16x16x32_bf16 v[98:101], v[142:145], v[212:215], v[98:101]
	v_mfma_f32_16x16x32_bf16 v[94:97], v[156:159], v[212:215], v[94:97]
	v_mfma_f32_16x16x32_bf16 v[78:81], v[142:145], v[220:223], v[78:81]
	v_mfma_f32_16x16x32_bf16 v[74:77], v[156:159], v[220:223], v[74:77]
	v_mfma_f32_16x16x32_bf16 v[130:133], v[152:155], v[200:203], v[130:133]
	v_mfma_f32_16x16x32_bf16 v[126:129], v[160:163], v[200:203], v[126:129]
	v_mfma_f32_16x16x32_bf16 v[114:117], v[152:155], v[208:211], v[114:117]
	v_mfma_f32_16x16x32_bf16 v[110:113], v[160:163], v[208:211], v[110:113]
	v_mfma_f32_16x16x32_bf16 v[98:101], v[152:155], v[216:219], v[98:101]
	v_mfma_f32_16x16x32_bf16 v[94:97], v[160:163], v[216:219], v[94:97]
	v_mfma_f32_16x16x32_bf16 v[78:81], v[152:155], v[224:227], v[78:81]
	v_mfma_f32_16x16x32_bf16 v[74:77], v[160:163], v[224:227], v[74:77]
	v_mfma_f32_16x16x32_bf16 v[122:125], v[164:167], v[184:187], v[122:125]
	v_mfma_f32_16x16x32_bf16 v[118:121], v[172:175], v[184:187], v[118:121]
	v_mfma_f32_16x16x32_bf16 v[106:109], v[164:167], v[204:207], v[106:109]
	v_mfma_f32_16x16x32_bf16 v[102:105], v[172:175], v[204:207], v[102:105]
	v_mfma_f32_16x16x32_bf16 v[90:93], v[164:167], v[212:215], v[90:93]
	v_mfma_f32_16x16x32_bf16 v[86:89], v[172:175], v[212:215], v[86:89]
	v_mfma_f32_16x16x32_bf16 v[70:73], v[164:167], v[220:223], v[70:73]
	v_mfma_f32_16x16x32_bf16 v[66:69], v[172:175], v[220:223], v[66:69]
	v_mfma_f32_16x16x32_bf16 v[122:125], v[168:171], v[200:203], v[122:125]
	v_mfma_f32_16x16x32_bf16 v[118:121], v[180:183], v[200:203], v[118:121]
	v_mfma_f32_16x16x32_bf16 v[106:109], v[168:171], v[208:211], v[106:109]
	v_mfma_f32_16x16x32_bf16 v[102:105], v[180:183], v[208:211], v[102:105]
	v_mfma_f32_16x16x32_bf16 v[90:93], v[168:171], v[216:219], v[90:93]
	v_mfma_f32_16x16x32_bf16 v[86:89], v[180:183], v[216:219], v[86:89]
	v_mfma_f32_16x16x32_bf16 v[70:73], v[168:171], v[224:227], v[70:73]
	v_mfma_f32_16x16x32_bf16 v[66:69], v[180:183], v[224:227], v[66:69]
	s_barrier
; #define PG8_STAGE(bufoff, gbase, voff) do { _Pragma("unroll") for (int _i = 0; _i < 2; ++_i) \
;         __builtin_amdgcn_global_load_lds((const unsigned*)((const char*)(gbase) + (voff)[_i]), (PG8_LAS unsigned*)(lds + (bufoff) + ldsw + _i * 8192), 16, 0, 0); } while (0)
; #define PG8_LDA(dst, b, h) do { _Pragma("unroll") for (int m = 0; m < 4; ++m) _Pragma("unroll") for (int k = 0; k < 2; ++k) dst[m][k] = *(const PG8_LAS bf16x8*)(lds + PG8_SA(b, h) + aoff + m * 2048 + k * 1024); } while (0)
; #define PG8_MMA(ai, bj, At, Bt) do { __builtin_amdgcn_s_setprio(1); _Pragma("unroll") for (int m = 0; m < 4; ++m) _Pragma("unroll") for (int n = 0; n < 2; ++n) _Pragma("unroll") for (int k = 0; k < 2; ++k) \
;         acc[ai][bj][m][n] = __builtin_amdgcn_mfma_f32_16x16x32_bf16(Bt[n][k], At[m][k], acc[ai][bj][m][n], 0, 0, 0); __builtin_amdgcn_s_setprio(0); } while (0)
; #define PG8_WAIT_V(n) asm volatile("s_waitcnt vmcnt(" #n ")" ::: "memory")
; #define PG8_WAIT_L(n) asm volatile("s_waitcnt lgkmcnt(" #n ")" ::: "memory")
; #define PG8_BAR __builtin_amdgcn_s_barrier()
; #define PG8_SCHED __builtin_amdgcn_sched_barrier(0)
; template <class Epi, class Sched, bool ALIGN_EPI = false, bool SP2 = false>
; __device__ __forceinline__ void gemm_phase(PG8_LAS unsigned char* lds, const Gemm g, const Sched& S, const Epi& E) {
;     ...
;             PG8_LDA(At, 1, 1); PG8_STAGE(PG8_SB(1, 0), b3, voffB); PG8_STAGE(PG8_SB(1, 1), b3 + hstep, voffB); PG8_STAGE(PG8_SA(1, 0), a3, voffA);
;             PG8_WAIT_V(8); PG8_WAIT_L(0); PG8_BAR; PG8_MMA(1, 0, At, B0); PG8_MMA(1, 1, At, B1); PG8_BAR; PG8_SCHED;
;     ...
;         if constexpr (ALIGN_EPI) { if (wr == 0) PG8_BAR; }
	s_setprio 0
	s_add_i32 s65, s65, s28
	v_lshl_add_u64 v[146:147], v[146:147], 0, s[38:39]
	s_mov_b32 m0, s65
	ds_read_b128 v[184:187], v150 offset:49152
	ds_read_b128 v[200:203], v150 offset:50176
	ds_read_b128 v[204:207], v150 offset:51200
	ds_read_b128 v[208:211], v150 offset:52224
	ds_read_b128 v[212:215], v150 offset:53248
	ds_read_b128 v[216:219], v150 offset:54272
	ds_read_b128 v[220:223], v150 offset:55296
	ds_read_b128 v[224:227], v150 offset:56320
	global_load_lds_dwordx4 v[146:147], off
	s_add_i32 m0, s65, 0x2000
	s_add_u32 s68, s68, 0x40080
	v_lshl_add_u64 v[146:147], v[176:177], 0, s[38:39]
	s_addc_u32 s69, s69, 0
	s_add_i32 s65, s72, s28
	global_load_lds_dwordx4 v[146:147], off
	v_lshl_add_u64 v[146:147], s[68:69], 0, v[134:135]
	s_mov_b32 m0, s65
	s_nop 0
	global_load_lds_dwordx4 v[146:147], off
	v_lshl_add_u64 v[146:147], s[68:69], 0, v[136:137]
	s_add_i32 m0, s65, 0x2000
	s_nop 0
	global_load_lds_dwordx4 v[146:147], off
	v_lshl_add_u64 v[146:147], v[228:229], 0, s[38:39]
	s_mov_b32 m0, s41
	s_nop 0
	global_load_lds_dwordx4 v[146:147], off
	v_lshl_add_u64 v[146:147], v[230:231], 0, s[38:39]
	s_mov_b32 m0, s42
	s_nop 0
	global_load_lds_dwordx4 v[146:147], off
	s_waitcnt vmcnt(8)
	s_waitcnt lgkmcnt(0)
	s_setprio 1
	s_barrier
	v_mfma_f32_16x16x32_bf16 v[62:65], v[142:145], v[184:187], v[62:65]
	v_mfma_f32_16x16x32_bf16 v[58:61], v[156:159], v[184:187], v[58:61]
	v_mfma_f32_16x16x32_bf16 v[46:49], v[142:145], v[204:207], v[46:49]
	v_mfma_f32_16x16x32_bf16 v[42:45], v[156:159], v[204:207], v[42:45]
	v_mfma_f32_16x16x32_bf16 v[30:33], v[142:145], v[212:215], v[30:33]
	v_mfma_f32_16x16x32_bf16 v[26:29], v[156:159], v[212:215], v[26:29]
	v_mfma_f32_16x16x32_bf16 v[14:17], v[142:145], v[220:223], v[14:17]
	v_mfma_f32_16x16x32_bf16 v[10:13], v[156:159], v[220:223], v[10:13]
	v_mfma_f32_16x16x32_bf16 v[62:65], v[152:155], v[200:203], v[62:65]
	v_mfma_f32_16x16x32_bf16 v[58:61], v[160:163], v[200:203], v[58:61]
	v_mfma_f32_16x16x32_bf16 v[46:49], v[152:155], v[208:211], v[46:49]
	v_mfma_f32_16x16x32_bf16 v[42:45], v[160:163], v[208:211], v[42:45]
	v_mfma_f32_16x16x32_bf16 v[30:33], v[152:155], v[216:219], v[30:33]
	v_mfma_f32_16x16x32_bf16 v[26:29], v[160:163], v[216:219], v[26:29]
	v_mfma_f32_16x16x32_bf16 v[14:17], v[152:155], v[224:227], v[14:17]
	v_mfma_f32_16x16x32_bf16 v[10:13], v[160:163], v[224:227], v[10:13]
	v_mfma_f32_16x16x32_bf16 v[54:57], v[164:167], v[184:187], v[54:57]
	v_mfma_f32_16x16x32_bf16 v[50:53], v[172:175], v[184:187], v[50:53]
	v_mfma_f32_16x16x32_bf16 v[38:41], v[164:167], v[204:207], v[38:41]
	v_mfma_f32_16x16x32_bf16 v[34:37], v[172:175], v[204:207], v[34:37]
	v_mfma_f32_16x16x32_bf16 v[22:25], v[164:167], v[212:215], v[22:25]
	v_mfma_f32_16x16x32_bf16 v[18:21], v[172:175], v[212:215], v[18:21]
	v_mfma_f32_16x16x32_bf16 v[6:9], v[164:167], v[220:223], v[6:9]
	v_mfma_f32_16x16x32_bf16 v[2:5], v[172:175], v[220:223], v[2:5]
	v_mfma_f32_16x16x32_bf16 v[54:57], v[168:171], v[200:203], v[54:57]
	v_mfma_f32_16x16x32_bf16 v[50:53], v[180:183], v[200:203], v[50:53]
	v_mfma_f32_16x16x32_bf16 v[38:41], v[168:171], v[208:211], v[38:41]
	v_mfma_f32_16x16x32_bf16 v[34:37], v[180:183], v[208:211], v[34:37]
	v_mfma_f32_16x16x32_bf16 v[22:25], v[168:171], v[216:219], v[22:25]
	v_mfma_f32_16x16x32_bf16 v[18:21], v[180:183], v[216:219], v[18:21]
	v_mfma_f32_16x16x32_bf16 v[6:9], v[168:171], v[224:227], v[6:9]
	v_mfma_f32_16x16x32_bf16 v[2:5], v[180:183], v[224:227], v[2:5]
	s_barrier
	s_setprio 0
	s_add_i32 s63, s63, 2
	s_add_u32 s55, s55, 0x100
	s_addc_u32 s56, s56, 0
	s_add_u32 s66, s66, 0x100
	s_addc_u32 s67, s67, 0
	s_cmp_gt_u32 s63, 13
	s_cbranch_scc0 .LBB0_770
	s_and_b64 vcc, exec, s[20:21]
	s_cbranch_vccz .LBB0_773
	s_barrier

; #define PG8_STAGE(bufoff, gbase, voff) do { _Pragma("unroll") for (int _i = 0; _i < 2; ++_i) \
;         __builtin_amdgcn_global_load_lds((const unsigned*)((const char*)(gbase) + (voff)[_i]), (PG8_LAS unsigned*)(lds + (bufoff) + ldsw + _i * 8192), 16, 0, 0); } while (0)
; #define PG8_LDA(dst, b, h) do { _Pragma("unroll") for (int m = 0; m < 4; ++m) _Pragma("unroll") for (int k = 0; k < 2; ++k) dst[m][k] = *(const PG8_LAS bf16x8*)(lds + PG8_SA(b, h) + aoff + m * 2048 + k * 1024); } while (0)
; #define PG8_LDB(dst, b, h) do { _Pragma("unroll") for (int n = 0; n < 2; ++n) _Pragma("unroll") for (int k = 0; k < 2; ++k) dst[n][k] = *(const PG8_LAS bf16x8*)(lds + PG8_SB(b, h) + boff + n * 2048 + k * 1024); } while (0)
; #define PG8_MMA(ai, bj, At, Bt) do { __builtin_amdgcn_s_setprio(1); _Pragma("unroll") for (int m = 0; m < 4; ++m) _Pragma("unroll") for (int n = 0; n < 2; ++n) _Pragma("unroll") for (int k = 0; k < 2; ++k) \
;         acc[ai][bj][m][n] = __builtin_amdgcn_mfma_f32_16x16x32_bf16(Bt[n][k], At[m][k], acc[ai][bj][m][n], 0, 0, 0); __builtin_amdgcn_s_setprio(0); } while (0)
; #define PG8_WAIT_V(n) asm volatile("s_waitcnt vmcnt(" #n ")" ::: "memory")
; #define PG8_WAIT_L(n) asm volatile("s_waitcnt lgkmcnt(" #n ")" ::: "memory")
; template <class Epi, class Sched, bool ALIGN_EPI = false, bool SP2 = false>
; __device__ __forceinline__ void gemm_phase(PG8_LAS unsigned char* lds, const Gemm g, const Sched& S, const Epi& E) {
;     ...
;             const bool last = (t == nt - 2);
;             const char* a1 = cA + (size_t)(t + 1) * kstep;
;             const char* a2 = last ? nA : cA + (size_t)(t + 2) * kstep; const char* b2 = last ? nB : cB + (size_t)(t + 2) * kstep;
;             const char* a3 = a2 + kstep; const char* b3 = b2 + kstep;
;             if (last && has_next) S.a_ready(nxt);
;             if constexpr (SP2) {
;             PG8_LDB(B0, 0, 0); PG8_LDB(B1, 0, 1); PG8_SCHED; PG8_LDA(At, 0, 0); PG8_STAGE(PG8_SA(1, 1), a1 + hstep, voffA);
;             PG8_WAIT_V(8); PG8_WAIT_L(0); PG8_BAR; PG8_MMA(0, 0, At, B0); PG8_MMA(0, 1, At, B1); PG8_BAR; PG8_SCHED;
;             PG8_LDA(At, 0, 1); PG8_STAGE(PG8_SB(0, 0), b2, voffB); PG8_STAGE(PG8_SB(0, 1), b2 + hstep, voffB); PG8_STAGE(PG8_SA(0, 0), a2, voffA);
;             PG8_WAIT_V(8); PG8_WAIT_L(0); PG8_BAR; PG8_MMA(1, 0, At, B0); PG8_MMA(1, 1, At, B1); PG8_BAR; PG8_SCHED;
.LBB0_856:
	s_add_u32 s78, s76, 0xfffc0080
	s_addc_u32 s79, s77, -1
	s_add_i32 s84, 0, 0x10000
	s_cmp_eq_u32 s83, 12
	s_cselect_b32 s81, s56, s79
	s_cselect_b32 s80, s67, s78
	s_cselect_b32 s79, s65, s82
	s_cselect_b32 s78, s73, s75
	s_add_i32 s86, 0, 0x14000
	v_add_u32_e32 v146, s84, v177
	v_add_u32_e32 v174, s86, v177
	ds_read_b128 v[134:137], v146
	ds_read_b128 v[138:141], v146 offset:1024
	ds_read_b128 v[142:145], v146 offset:2048
	ds_read_b128 v[146:149], v146 offset:3072
	ds_read_b128 v[162:165], v174
	ds_read_b128 v[166:169], v174 offset:1024
	ds_read_b128 v[170:173], v174 offset:2048
	ds_read_b128 v[182:185], v174 offset:3072
	v_lshl_add_u64 v[174:175], s[76:77], 0, v[160:161]
	s_add_i32 m0, s36, 0xc000
	ds_read_b128 v[200:203], v180
	ds_read_b128 v[204:207], v180 offset:1024
	ds_read_b128 v[208:211], v180 offset:2048
	ds_read_b128 v[212:215], v180 offset:3072
	ds_read_b128 v[216:219], v180 offset:4096
	ds_read_b128 v[220:223], v180 offset:5120
	ds_read_b128 v[224:227], v180 offset:6144
	ds_read_b128 v[228:231], v180 offset:7168
	global_load_lds_dwordx4 v[174:175], off
	v_lshl_add_u64 v[174:175], s[76:77], 0, v[158:159]
	s_add_i32 m0, s36, 0xe000
	s_nop 0
	global_load_lds_dwordx4 v[174:175], off
	s_waitcnt vmcnt(8)
	s_waitcnt lgkmcnt(0)
	s_setprio 1
	s_barrier
	v_mfma_f32_16x16x32_bf16 v[130:133], v[134:137], v[200:203], v[130:133]
	v_mfma_f32_16x16x32_bf16 v[102:105], v[142:145], v[200:203], v[102:105]
	v_mfma_f32_16x16x32_bf16 v[126:129], v[134:137], v[208:211], v[126:129]
	v_mfma_f32_16x16x32_bf16 v[98:101], v[142:145], v[208:211], v[98:101]
	v_mfma_f32_16x16x32_bf16 v[122:125], v[134:137], v[216:219], v[122:125]
	v_mfma_f32_16x16x32_bf16 v[90:93], v[142:145], v[216:219], v[90:93]
	v_mfma_f32_16x16x32_bf16 v[118:121], v[134:137], v[224:227], v[118:121]
	v_mfma_f32_16x16x32_bf16 v[86:89], v[142:145], v[224:227], v[86:89]
	v_mfma_f32_16x16x32_bf16 v[130:133], v[138:141], v[204:207], v[130:133]
	v_mfma_f32_16x16x32_bf16 v[102:105], v[146:149], v[204:207], v[102:105]
	v_mfma_f32_16x16x32_bf16 v[126:129], v[138:141], v[212:215], v[126:129]
	v_mfma_f32_16x16x32_bf16 v[98:101], v[146:149], v[212:215], v[98:101]
	v_mfma_f32_16x16x32_bf16 v[122:125], v[138:141], v[220:223], v[122:125]
	v_mfma_f32_16x16x32_bf16 v[90:93], v[146:149], v[220:223], v[90:93]
	v_mfma_f32_16x16x32_bf16 v[118:121], v[138:141], v[228:231], v[118:121]
	v_mfma_f32_16x16x32_bf16 v[86:89], v[146:149], v[228:231], v[86:89]
	v_mfma_f32_16x16x32_bf16 v[94:97], v[162:165], v[200:203], v[94:97]
	v_mfma_f32_16x16x32_bf16 v[66:69], v[170:173], v[200:203], v[66:69]
	v_mfma_f32_16x16x32_bf16 v[114:117], v[162:165], v[208:211], v[114:117]
	v_mfma_f32_16x16x32_bf16 v[78:81], v[170:173], v[208:211], v[78:81]
	v_mfma_f32_16x16x32_bf16 v[110:113], v[162:165], v[216:219], v[110:113]
	v_mfma_f32_16x16x32_bf16 v[74:77], v[170:173], v[216:219], v[74:77]
	v_mfma_f32_16x16x32_bf16 v[106:109], v[162:165], v[224:227], v[106:109]
	v_mfma_f32_16x16x32_bf16 v[70:73], v[170:173], v[224:227], v[70:73]
	v_mfma_f32_16x16x32_bf16 v[94:97], v[166:169], v[204:207], v[94:97]
	v_mfma_f32_16x16x32_bf16 v[66:69], v[182:185], v[204:207], v[66:69]
	v_mfma_f32_16x16x32_bf16 v[114:117], v[166:169], v[212:215], v[114:117]
	v_mfma_f32_16x16x32_bf16 v[78:81], v[182:185], v[212:215], v[78:81]
	v_mfma_f32_16x16x32_bf16 v[110:113], v[166:169], v[220:223], v[110:113]
	v_mfma_f32_16x16x32_bf16 v[74:77], v[182:185], v[220:223], v[74:77]
	v_mfma_f32_16x16x32_bf16 v[106:109], v[166:169], v[228:231], v[106:109]
	v_mfma_f32_16x16x32_bf16 v[70:73], v[182:185], v[228:231], v[70:73]
	s_barrier
	s_setprio 0
	s_add_i32 s84, s84, s34
	v_lshl_add_u64 v[174:175], s[78:79], 0, v[152:153]
	s_mov_b32 m0, s84
	ds_read_b128 v[200:203], v180 offset:16384
	ds_read_b128 v[204:207], v180 offset:17408
	ds_read_b128 v[208:211], v180 offset:18432
	ds_read_b128 v[212:215], v180 offset:19456
	ds_read_b128 v[216:219], v180 offset:20480
	ds_read_b128 v[220:223], v180 offset:21504
	ds_read_b128 v[224:227], v180 offset:22528
	ds_read_b128 v[228:231], v180 offset:23552
	global_load_lds_dwordx4 v[174:175], off
	s_add_i32 m0, s84, 0x2000
	s_add_u32 s84, s78, 0x40000
	v_lshl_add_u64 v[186:187], s[78:79], 0, v[156:157]
	s_addc_u32 s85, s79, 0
	s_add_i32 s86, s86, s34
	global_load_lds_dwordx4 v[186:187], off
	v_lshl_add_u64 v[232:233], s[84:85], 0, v[152:153]
	s_mov_b32 m0, s86
	v_lshl_add_u64 v[234:235], s[80:81], 0, v[154:155]
	global_load_lds_dwordx4 v[232:233], off
	v_lshl_add_u64 v[232:233], s[84:85], 0, v[156:157]
	s_add_i32 m0, s86, 0x2000
	s_nop 0
	global_load_lds_dwordx4 v[232:233], off
	v_lshl_add_u64 v[232:233], s[80:81], 0, v[150:151]
	s_mov_b32 m0, s36
	s_nop 0
	global_load_lds_dwordx4 v[232:233], off
	s_mov_b32 m0, s37
	s_nop 0
	global_load_lds_dwordx4 v[234:235], off
	s_waitcnt vmcnt(8)
	s_waitcnt lgkmcnt(0)
	s_setprio 1
	s_barrier
; #define PG8_STAGE(bufoff, gbase, voff) do { _Pragma("unroll") for (int _i = 0; _i < 2; ++_i) \
;         __builtin_amdgcn_global_load_lds((const unsigned*)((const char*)(gbase) + (voff)[_i]), (PG8_LAS unsigned*)(lds + (bufoff) + ldsw + _i * 8192), 16, 0, 0); } while (0)
; #define PG8_LDA(dst, b, h) do { _Pragma("unroll") for (int m = 0; m < 4; ++m) _Pragma("unroll") for (int k = 0; k < 2; ++k) dst[m][k] = *(const PG8_LAS bf16x8*)(lds + PG8_SA(b, h) + aoff + m * 2048 + k * 1024); } while (0)
; #define PG8_LDB(dst, b, h) do { _Pragma("unroll") for (int n = 0; n < 2; ++n) _Pragma("unroll") for (int k = 0; k < 2; ++k) dst[n][k] = *(const PG8_LAS bf16x8*)(lds + PG8_SB(b, h) + boff + n * 2048 + k * 1024); } while (0)
; #define PG8_MMA(ai, bj, At, Bt) do { __builtin_amdgcn_s_setprio(1); _Pragma("unroll") for (int m = 0; m < 4; ++m) _Pragma("unroll") for (int n = 0; n < 2; ++n) _Pragma("unroll") for (int k = 0; k < 2; ++k) \
;         acc[ai][bj][m][n] = __builtin_amdgcn_mfma_f32_16x16x32_bf16(Bt[n][k], At[m][k], acc[ai][bj][m][n], 0, 0, 0); __builtin_amdgcn_s_setprio(0); } while (0)
; #define PG8_WAIT_V(n) asm volatile("s_waitcnt vmcnt(" #n ")" ::: "memory")
; #define PG8_WAIT_L(n) asm volatile("s_waitcnt lgkmcnt(" #n ")" ::: "memory")
; #define PG8_BAR __builtin_amdgcn_s_barrier()
; #define PG8_SCHED __builtin_amdgcn_sched_barrier(0)
; template <class Epi, class Sched, bool ALIGN_EPI = false, bool SP2 = false>
; __device__ __forceinline__ void gemm_phase(PG8_LAS unsigned char* lds, const Gemm g, const Sched& S, const Epi& E) {
;     ...
;             PG8_WAIT_V(8); PG8_WAIT_L(0); PG8_BAR; PG8_MMA(1, 0, At, B0); PG8_MMA(1, 1, At, B1); PG8_BAR; PG8_SCHED;
;             PG8_LDB(B0, 1, 0); PG8_LDB(B1, 1, 1); PG8_SCHED; PG8_LDA(At, 1, 0); PG8_STAGE(PG8_SA(0, 1), a2 + hstep, voffA);
;             PG8_WAIT_V(8); PG8_WAIT_L(0); PG8_BAR; PG8_MMA(0, 0, At, B0); PG8_MMA(0, 1, At, B1); PG8_BAR; PG8_SCHED;
	v_mfma_f32_16x16x32_bf16 v[62:65], v[134:137], v[200:203], v[62:65]
	v_mfma_f32_16x16x32_bf16 v[30:33], v[142:145], v[200:203], v[30:33]
	v_mfma_f32_16x16x32_bf16 v[58:61], v[134:137], v[208:211], v[58:61]
	v_mfma_f32_16x16x32_bf16 v[26:29], v[142:145], v[208:211], v[26:29]
	v_mfma_f32_16x16x32_bf16 v[54:57], v[134:137], v[216:219], v[54:57]
	v_mfma_f32_16x16x32_bf16 v[22:25], v[142:145], v[216:219], v[22:25]
	v_mfma_f32_16x16x32_bf16 v[50:53], v[134:137], v[224:227], v[50:53]
	v_mfma_f32_16x16x32_bf16 v[18:21], v[142:145], v[224:227], v[18:21]
	v_mfma_f32_16x16x32_bf16 v[62:65], v[138:141], v[204:207], v[62:65]
	v_mfma_f32_16x16x32_bf16 v[30:33], v[146:149], v[204:207], v[30:33]
	v_mfma_f32_16x16x32_bf16 v[58:61], v[138:141], v[212:215], v[58:61]
	v_mfma_f32_16x16x32_bf16 v[26:29], v[146:149], v[212:215], v[26:29]
	v_mfma_f32_16x16x32_bf16 v[54:57], v[138:141], v[220:223], v[54:57]
	v_mfma_f32_16x16x32_bf16 v[22:25], v[146:149], v[220:223], v[22:25]
	v_mfma_f32_16x16x32_bf16 v[50:53], v[138:141], v[228:231], v[50:53]
	v_mfma_f32_16x16x32_bf16 v[18:21], v[146:149], v[228:231], v[18:21]
	v_mfma_f32_16x16x32_bf16 v[34:37], v[162:165], v[200:203], v[34:37]
	v_mfma_f32_16x16x32_bf16 v[2:5], v[170:173], v[200:203], v[2:5]
	v_mfma_f32_16x16x32_bf16 v[46:49], v[162:165], v[208:211], v[46:49]
	v_mfma_f32_16x16x32_bf16 v[14:17], v[170:173], v[208:211], v[14:17]
	v_mfma_f32_16x16x32_bf16 v[42:45], v[162:165], v[216:219], v[42:45]
	v_mfma_f32_16x16x32_bf16 v[10:13], v[170:173], v[216:219], v[10:13]
	v_mfma_f32_16x16x32_bf16 v[38:41], v[162:165], v[224:227], v[38:41]
	v_mfma_f32_16x16x32_bf16 v[6:9], v[170:173], v[224:227], v[6:9]
	v_mfma_f32_16x16x32_bf16 v[34:37], v[166:169], v[204:207], v[34:37]
	v_mfma_f32_16x16x32_bf16 v[2:5], v[182:185], v[204:207], v[2:5]
	v_mfma_f32_16x16x32_bf16 v[46:49], v[166:169], v[212:215], v[46:49]
	v_mfma_f32_16x16x32_bf16 v[14:17], v[182:185], v[212:215], v[14:17]
	v_mfma_f32_16x16x32_bf16 v[42:45], v[166:169], v[220:223], v[42:45]
	v_mfma_f32_16x16x32_bf16 v[10:13], v[182:185], v[220:223], v[10:13]
	v_mfma_f32_16x16x32_bf16 v[38:41], v[166:169], v[228:231], v[38:41]
	v_mfma_f32_16x16x32_bf16 v[6:9], v[182:185], v[228:231], v[6:9]
	s_barrier
	s_setprio 0
	s_add_i32 s84, 0, 0x18000
	s_add_i32 s85, 0, 0x1c000
	v_add_u32_e32 v146, s84, v177
	v_add_u32_e32 v181, s85, v177
	ds_read_b128 v[134:137], v146
	ds_read_b128 v[138:141], v146 offset:1024
	ds_read_b128 v[142:145], v146 offset:2048
	ds_read_b128 v[146:149], v146 offset:3072
	ds_read_b128 v[162:165], v181
	ds_read_b128 v[166:169], v181 offset:1024
	ds_read_b128 v[170:173], v181 offset:2048
	ds_read_b128 v[182:185], v181 offset:3072
	s_add_u32 s80, s80, 0x40000
	s_addc_u32 s81, s81, 0
	s_mov_b32 m0, s40
	v_lshl_add_u64 v[236:237], s[80:81], 0, v[150:151]
	ds_read_b128 v[200:203], v180 offset:32768
	ds_read_b128 v[204:207], v180 offset:33792
	ds_read_b128 v[208:211], v180 offset:34816
	ds_read_b128 v[212:215], v180 offset:35840
	ds_read_b128 v[216:219], v180 offset:36864
	ds_read_b128 v[220:223], v180 offset:37888
	ds_read_b128 v[224:227], v180 offset:38912
	ds_read_b128 v[228:231], v180 offset:39936
	global_load_lds_dwordx4 v[236:237], off
	v_lshl_add_u64 v[236:237], s[80:81], 0, v[154:155]
	s_mov_b32 m0, s41
	s_nop 0
	global_load_lds_dwordx4 v[236:237], off
	s_waitcnt vmcnt(8)
	s_waitcnt lgkmcnt(0)
	s_setprio 1
	s_barrier
	v_mfma_f32_16x16x32_bf16 v[130:133], v[134:137], v[200:203], v[130:133]
	v_mfma_f32_16x16x32_bf16 v[102:105], v[142:145], v[200:203], v[102:105]
	v_mfma_f32_16x16x32_bf16 v[126:129], v[134:137], v[208:211], v[126:129]
	v_mfma_f32_16x16x32_bf16 v[98:101], v[142:145], v[208:211], v[98:101]
	v_mfma_f32_16x16x32_bf16 v[122:125], v[134:137], v[216:219], v[122:125]
	v_mfma_f32_16x16x32_bf16 v[90:93], v[142:145], v[216:219], v[90:93]
	v_mfma_f32_16x16x32_bf16 v[118:121], v[134:137], v[224:227], v[118:121]
	v_mfma_f32_16x16x32_bf16 v[86:89], v[142:145], v[224:227], v[86:89]
	v_mfma_f32_16x16x32_bf16 v[130:133], v[138:141], v[204:207], v[130:133]
	v_mfma_f32_16x16x32_bf16 v[102:105], v[146:149], v[204:207], v[102:105]
	v_mfma_f32_16x16x32_bf16 v[126:129], v[138:141], v[212:215], v[126:129]
	v_mfma_f32_16x16x32_bf16 v[98:101], v[146:149], v[212:215], v[98:101]
	v_mfma_f32_16x16x32_bf16 v[122:125], v[138:141], v[220:223], v[122:125]
	v_mfma_f32_16x16x32_bf16 v[90:93], v[146:149], v[220:223], v[90:93]
	v_mfma_f32_16x16x32_bf16 v[118:121], v[138:141], v[228:231], v[118:121]
	v_mfma_f32_16x16x32_bf16 v[86:89], v[146:149], v[228:231], v[86:89]
	v_mfma_f32_16x16x32_bf16 v[94:97], v[162:165], v[200:203], v[94:97]
	v_mfma_f32_16x16x32_bf16 v[66:69], v[170:173], v[200:203], v[66:69]
	v_mfma_f32_16x16x32_bf16 v[114:117], v[162:165], v[208:211], v[114:117]
	v_mfma_f32_16x16x32_bf16 v[78:81], v[170:173], v[208:211], v[78:81]
	v_mfma_f32_16x16x32_bf16 v[110:113], v[162:165], v[216:219], v[110:113]
	v_mfma_f32_16x16x32_bf16 v[74:77], v[170:173], v[216:219], v[74:77]
	v_mfma_f32_16x16x32_bf16 v[106:109], v[162:165], v[224:227], v[106:109]
	v_mfma_f32_16x16x32_bf16 v[70:73], v[170:173], v[224:227], v[70:73]
	v_mfma_f32_16x16x32_bf16 v[94:97], v[166:169], v[204:207], v[94:97]
	v_mfma_f32_16x16x32_bf16 v[66:69], v[182:185], v[204:207], v[66:69]
	v_mfma_f32_16x16x32_bf16 v[114:117], v[166:169], v[212:215], v[114:117]
	v_mfma_f32_16x16x32_bf16 v[78:81], v[182:185], v[212:215], v[78:81]
	v_mfma_f32_16x16x32_bf16 v[110:113], v[166:169], v[220:223], v[110:113]
	v_mfma_f32_16x16x32_bf16 v[74:77], v[182:185], v[220:223], v[74:77]
	v_mfma_f32_16x16x32_bf16 v[106:109], v[166:169], v[228:231], v[106:109]
	v_mfma_f32_16x16x32_bf16 v[70:73], v[182:185], v[228:231], v[70:73]
	s_barrier
; #define PG8_STAGE(bufoff, gbase, voff) do { _Pragma("unroll") for (int _i = 0; _i < 2; ++_i) \
;         __builtin_amdgcn_global_load_lds((const unsigned*)((const char*)(gbase) + (voff)[_i]), (PG8_LAS unsigned*)(lds + (bufoff) + ldsw + _i * 8192), 16, 0, 0); } while (0)
; #define PG8_LDA(dst, b, h) do { _Pragma("unroll") for (int m = 0; m < 4; ++m) _Pragma("unroll") for (int k = 0; k < 2; ++k) dst[m][k] = *(const PG8_LAS bf16x8*)(lds + PG8_SA(b, h) + aoff + m * 2048 + k * 1024); } while (0)
; #define PG8_MMA(ai, bj, At, Bt) do { __builtin_amdgcn_s_setprio(1); _Pragma("unroll") for (int m = 0; m < 4; ++m) _Pragma("unroll") for (int n = 0; n < 2; ++n) _Pragma("unroll") for (int k = 0; k < 2; ++k) \
;         acc[ai][bj][m][n] = __builtin_amdgcn_mfma_f32_16x16x32_bf16(Bt[n][k], At[m][k], acc[ai][bj][m][n], 0, 0, 0); __builtin_amdgcn_s_setprio(0); } while (0)
; #define PG8_WAIT_V(n) asm volatile("s_waitcnt vmcnt(" #n ")" ::: "memory")
; #define PG8_WAIT_L(n) asm volatile("s_waitcnt lgkmcnt(" #n ")" ::: "memory")
; #define PG8_BAR __builtin_amdgcn_s_barrier()
; #define PG8_SCHED __builtin_amdgcn_sched_barrier(0)
; template <class Epi, class Sched, bool ALIGN_EPI = false, bool SP2 = false>
; __device__ __forceinline__ void gemm_phase(PG8_LAS unsigned char* lds, const Gemm g, const Sched& S, const Epi& E) {
;     ...
;             PG8_LDA(At, 1, 1); PG8_STAGE(PG8_SB(1, 0), b3, voffB); PG8_STAGE(PG8_SB(1, 1), b3 + hstep, voffB); PG8_STAGE(PG8_SA(1, 0), a3, voffA);
;             PG8_WAIT_V(8); PG8_WAIT_L(0); PG8_BAR; PG8_MMA(1, 0, At, B0); PG8_MMA(1, 1, At, B1); PG8_BAR; PG8_SCHED;
;     ...
;         if constexpr (ALIGN_EPI) { if (wr == 0) PG8_BAR; }
	s_setprio 0
	s_add_i32 s80, s84, s34
	v_lshl_add_u64 v[174:175], v[174:175], 0, s[38:39]
	s_mov_b32 m0, s80
	ds_read_b128 v[200:203], v180 offset:49152
	ds_read_b128 v[204:207], v180 offset:50176
	ds_read_b128 v[208:211], v180 offset:51200
	ds_read_b128 v[212:215], v180 offset:52224
	ds_read_b128 v[216:219], v180 offset:53248
	ds_read_b128 v[220:223], v180 offset:54272
	ds_read_b128 v[224:227], v180 offset:55296
	ds_read_b128 v[228:231], v180 offset:56320
	global_load_lds_dwordx4 v[174:175], off
	s_add_i32 m0, s80, 0x2000
	s_add_u32 s78, s78, 0x40080
	v_lshl_add_u64 v[174:175], v[186:187], 0, s[38:39]
	s_addc_u32 s79, s79, 0
	s_add_i32 s80, s85, s34
	global_load_lds_dwordx4 v[174:175], off
	v_lshl_add_u64 v[174:175], s[78:79], 0, v[152:153]
	s_mov_b32 m0, s80
	s_nop 0
	global_load_lds_dwordx4 v[174:175], off
	v_lshl_add_u64 v[174:175], s[78:79], 0, v[156:157]
	s_add_i32 m0, s80, 0x2000
	s_nop 0
	global_load_lds_dwordx4 v[174:175], off
	v_lshl_add_u64 v[174:175], v[232:233], 0, s[38:39]
	s_mov_b32 m0, s52
	s_nop 0
	global_load_lds_dwordx4 v[174:175], off
	v_lshl_add_u64 v[174:175], v[234:235], 0, s[38:39]
	s_mov_b32 m0, s53
	s_nop 0
	global_load_lds_dwordx4 v[174:175], off
	s_waitcnt vmcnt(8)
	s_waitcnt lgkmcnt(0)
	s_setprio 1
	s_barrier
	v_mfma_f32_16x16x32_bf16 v[62:65], v[134:137], v[200:203], v[62:65]
	v_mfma_f32_16x16x32_bf16 v[30:33], v[142:145], v[200:203], v[30:33]
	v_mfma_f32_16x16x32_bf16 v[58:61], v[134:137], v[208:211], v[58:61]
	v_mfma_f32_16x16x32_bf16 v[26:29], v[142:145], v[208:211], v[26:29]
	v_mfma_f32_16x16x32_bf16 v[54:57], v[134:137], v[216:219], v[54:57]
	v_mfma_f32_16x16x32_bf16 v[22:25], v[142:145], v[216:219], v[22:25]
	v_mfma_f32_16x16x32_bf16 v[50:53], v[134:137], v[224:227], v[50:53]
	v_mfma_f32_16x16x32_bf16 v[18:21], v[142:145], v[224:227], v[18:21]
	v_mfma_f32_16x16x32_bf16 v[62:65], v[138:141], v[204:207], v[62:65]
	v_mfma_f32_16x16x32_bf16 v[30:33], v[146:149], v[204:207], v[30:33]
	v_mfma_f32_16x16x32_bf16 v[58:61], v[138:141], v[212:215], v[58:61]
	v_mfma_f32_16x16x32_bf16 v[26:29], v[146:149], v[212:215], v[26:29]
	v_mfma_f32_16x16x32_bf16 v[54:57], v[138:141], v[220:223], v[54:57]
	v_mfma_f32_16x16x32_bf16 v[22:25], v[146:149], v[220:223], v[22:25]
	v_mfma_f32_16x16x32_bf16 v[50:53], v[138:141], v[228:231], v[50:53]
	v_mfma_f32_16x16x32_bf16 v[18:21], v[146:149], v[228:231], v[18:21]
	v_mfma_f32_16x16x32_bf16 v[34:37], v[162:165], v[200:203], v[34:37]
	v_mfma_f32_16x16x32_bf16 v[2:5], v[170:173], v[200:203], v[2:5]
	v_mfma_f32_16x16x32_bf16 v[46:49], v[162:165], v[208:211], v[46:49]
	v_mfma_f32_16x16x32_bf16 v[14:17], v[170:173], v[208:211], v[14:17]
	v_mfma_f32_16x16x32_bf16 v[42:45], v[162:165], v[216:219], v[42:45]
	v_mfma_f32_16x16x32_bf16 v[10:13], v[170:173], v[216:219], v[10:13]
	v_mfma_f32_16x16x32_bf16 v[38:41], v[162:165], v[224:227], v[38:41]
	v_mfma_f32_16x16x32_bf16 v[6:9], v[170:173], v[224:227], v[6:9]
	v_mfma_f32_16x16x32_bf16 v[34:37], v[166:169], v[204:207], v[34:37]
	v_mfma_f32_16x16x32_bf16 v[2:5], v[182:185], v[204:207], v[2:5]
	v_mfma_f32_16x16x32_bf16 v[46:49], v[166:169], v[212:215], v[46:49]
	v_mfma_f32_16x16x32_bf16 v[14:17], v[182:185], v[212:215], v[14:17]
	v_mfma_f32_16x16x32_bf16 v[42:45], v[166:169], v[220:223], v[42:45]
	v_mfma_f32_16x16x32_bf16 v[10:13], v[182:185], v[220:223], v[10:13]
	v_mfma_f32_16x16x32_bf16 v[38:41], v[166:169], v[228:231], v[38:41]
	v_mfma_f32_16x16x32_bf16 v[6:9], v[182:185], v[228:231], v[6:9]
	s_barrier
	s_setprio 0
	s_add_i32 s83, s83, 2
	s_add_u32 s75, s75, 0x100
	s_addc_u32 s82, s82, 0
	s_add_u32 s76, s76, 0x100
	s_addc_u32 s77, s77, 0
	s_cmp_gt_u32 s83, 13
	s_cbranch_scc0 .LBB0_856
	s_and_b64 vcc, exec, s[58:59]
	s_cbranch_vccz .LBB0_859
	s_barrier

; #define PG8_STAGE(bufoff, gbase, voff) do { _Pragma("unroll") for (int _i = 0; _i < 2; ++_i) \
;         __builtin_amdgcn_global_load_lds((const unsigned*)((const char*)(gbase) + (voff)[_i]), (PG8_LAS unsigned*)(lds + (bufoff) + ldsw + _i * 8192), 16, 0, 0); } while (0)
; #define PG8_LDA(dst, b, h) do { _Pragma("unroll") for (int m = 0; m < 4; ++m) _Pragma("unroll") for (int k = 0; k < 2; ++k) dst[m][k] = *(const PG8_LAS bf16x8*)(lds + PG8_SA(b, h) + aoff + m * 2048 + k * 1024); } while (0)
; #define PG8_LDB(dst, b, h) do { _Pragma("unroll") for (int n = 0; n < 2; ++n) _Pragma("unroll") for (int k = 0; k < 2; ++k) dst[n][k] = *(const PG8_LAS bf16x8*)(lds + PG8_SB(b, h) + boff + n * 2048 + k * 1024); } while (0)
; #define PG8_MMA(ai, bj, At, Bt) do { __builtin_amdgcn_s_setprio(1); _Pragma("unroll") for (int m = 0; m < 4; ++m) _Pragma("unroll") for (int n = 0; n < 2; ++n) _Pragma("unroll") for (int k = 0; k < 2; ++k) \
;         acc[ai][bj][m][n] = __builtin_amdgcn_mfma_f32_16x16x32_bf16(Bt[n][k], At[m][k], acc[ai][bj][m][n], 0, 0, 0); __builtin_amdgcn_s_setprio(0); } while (0)
; #define PG8_WAIT_V(n) asm volatile("s_waitcnt vmcnt(" #n ")" ::: "memory")
; #define PG8_WAIT_L(n) asm volatile("s_waitcnt lgkmcnt(" #n ")" ::: "memory")
; template <class Epi, class Sched, bool ALIGN_EPI = false, bool SP2 = false>
; __device__ __forceinline__ void gemm_phase(PG8_LAS unsigned char* lds, const Gemm g, const Sched& S, const Epi& E) {
;     ...
;             const bool last = (t == nt - 2);
;             const char* a1 = cA + (size_t)(t + 1) * kstep;
;             const char* a2 = last ? nA : cA + (size_t)(t + 2) * kstep; const char* b2 = last ? nB : cB + (size_t)(t + 2) * kstep;
;             const char* a3 = a2 + kstep; const char* b3 = b2 + kstep;
;             if (last && has_next) S.a_ready(nxt);
;             if constexpr (SP2) {
;             PG8_LDB(B0, 0, 0); PG8_LDB(B1, 0, 1); PG8_SCHED; PG8_LDA(At, 0, 0); PG8_STAGE(PG8_SA(1, 1), a1 + hstep, voffA);
;             PG8_WAIT_V(8); PG8_WAIT_L(0); PG8_BAR; PG8_MMA(0, 0, At, B0); PG8_MMA(0, 1, At, B1); PG8_BAR; PG8_SCHED;
;             PG8_LDA(At, 0, 1); PG8_STAGE(PG8_SB(0, 0), b2, voffB); PG8_STAGE(PG8_SB(0, 1), b2 + hstep, voffB); PG8_STAGE(PG8_SA(0, 0), a2, voffA);
;             PG8_WAIT_V(8); PG8_WAIT_L(0); PG8_BAR; PG8_MMA(1, 0, At, B0); PG8_MMA(1, 1, At, B1); PG8_BAR; PG8_SCHED;
.LBB0_1035:
	s_add_u32 s24, s20, 0x100
	s_addc_u32 s25, s21, 0
	s_add_i32 s64, 0, 0x10000
	s_cmp_eq_u32 s63, 44
	s_cselect_b32 s59, s7, s25
	s_cselect_b32 s58, s6, s24
	v_add_u32_e32 v146, s64, v148
	s_cselect_b32 s27, s19, s62
	s_cselect_b32 s26, s18, s61
	s_add_i32 s65, 0, 0x14000
	ds_read_b128 v[142:145], v146
	ds_read_b128 v[152:155], v146 offset:1024
	ds_read_b128 v[156:159], v146 offset:2048
	ds_read_b128 v[160:163], v146 offset:3072
	v_add_u32_e32 v146, s65, v148
	ds_read_b128 v[164:167], v146
	ds_read_b128 v[168:171], v146 offset:1024
	ds_read_b128 v[172:175], v146 offset:2048
	ds_read_b128 v[180:183], v146 offset:3072
	v_lshl_add_u64 v[146:147], s[20:21], 0, v[140:141]
	s_add_i32 m0, s37, 0xc000
	ds_read_b128 v[184:187], v150
	ds_read_b128 v[200:203], v150 offset:1024
	ds_read_b128 v[204:207], v150 offset:2048
	ds_read_b128 v[208:211], v150 offset:3072
	ds_read_b128 v[212:215], v150 offset:4096
	ds_read_b128 v[216:219], v150 offset:5120
	ds_read_b128 v[220:223], v150 offset:6144
	ds_read_b128 v[224:227], v150 offset:7168
	global_load_lds_dwordx4 v[146:147], off
	v_lshl_add_u64 v[146:147], s[20:21], 0, v[138:139]
	s_add_i32 m0, s37, 0xe000
	s_nop 0
	global_load_lds_dwordx4 v[146:147], off
	s_waitcnt vmcnt(8)
	s_waitcnt lgkmcnt(0)
	s_setprio 1
	s_barrier
	v_mfma_f32_16x16x32_bf16 v[130:133], v[142:145], v[184:187], v[130:133]
	v_mfma_f32_16x16x32_bf16 v[126:129], v[156:159], v[184:187], v[126:129]
	v_mfma_f32_16x16x32_bf16 v[118:121], v[142:145], v[204:207], v[118:121]
	v_mfma_f32_16x16x32_bf16 v[110:113], v[156:159], v[204:207], v[110:113]
	v_mfma_f32_16x16x32_bf16 v[102:105], v[142:145], v[212:215], v[102:105]
	v_mfma_f32_16x16x32_bf16 v[94:97], v[156:159], v[212:215], v[94:97]
	v_mfma_f32_16x16x32_bf16 v[86:89], v[142:145], v[220:223], v[86:89]
	v_mfma_f32_16x16x32_bf16 v[74:77], v[156:159], v[220:223], v[74:77]
	v_mfma_f32_16x16x32_bf16 v[130:133], v[152:155], v[200:203], v[130:133]
	v_mfma_f32_16x16x32_bf16 v[126:129], v[160:163], v[200:203], v[126:129]
	v_mfma_f32_16x16x32_bf16 v[118:121], v[152:155], v[208:211], v[118:121]
	v_mfma_f32_16x16x32_bf16 v[110:113], v[160:163], v[208:211], v[110:113]
	v_mfma_f32_16x16x32_bf16 v[102:105], v[152:155], v[216:219], v[102:105]
	v_mfma_f32_16x16x32_bf16 v[94:97], v[160:163], v[216:219], v[94:97]
	v_mfma_f32_16x16x32_bf16 v[86:89], v[152:155], v[224:227], v[86:89]
	v_mfma_f32_16x16x32_bf16 v[74:77], v[160:163], v[224:227], v[74:77]
	v_mfma_f32_16x16x32_bf16 v[122:125], v[164:167], v[184:187], v[122:125]
	v_mfma_f32_16x16x32_bf16 v[114:117], v[172:175], v[184:187], v[114:117]
	v_mfma_f32_16x16x32_bf16 v[106:109], v[164:167], v[204:207], v[106:109]
	v_mfma_f32_16x16x32_bf16 v[98:101], v[172:175], v[204:207], v[98:101]
	v_mfma_f32_16x16x32_bf16 v[90:93], v[164:167], v[212:215], v[90:93]
	v_mfma_f32_16x16x32_bf16 v[78:81], v[172:175], v[212:215], v[78:81]
	v_mfma_f32_16x16x32_bf16 v[70:73], v[164:167], v[220:223], v[70:73]
	v_mfma_f32_16x16x32_bf16 v[66:69], v[172:175], v[220:223], v[66:69]
	v_mfma_f32_16x16x32_bf16 v[122:125], v[168:171], v[200:203], v[122:125]
	v_mfma_f32_16x16x32_bf16 v[114:117], v[180:183], v[200:203], v[114:117]
	v_mfma_f32_16x16x32_bf16 v[106:109], v[168:171], v[208:211], v[106:109]
	v_mfma_f32_16x16x32_bf16 v[98:101], v[180:183], v[208:211], v[98:101]
	v_mfma_f32_16x16x32_bf16 v[90:93], v[168:171], v[216:219], v[90:93]
	v_mfma_f32_16x16x32_bf16 v[78:81], v[180:183], v[216:219], v[78:81]
	v_mfma_f32_16x16x32_bf16 v[70:73], v[168:171], v[224:227], v[70:73]
	v_mfma_f32_16x16x32_bf16 v[66:69], v[180:183], v[224:227], v[66:69]
	s_barrier
	s_setprio 0
	s_add_i32 s20, s64, s28
	v_lshl_add_u64 v[146:147], s[26:27], 0, v[136:137]
	s_mov_b32 m0, s20
	ds_read_b128 v[184:187], v150 offset:16384
	ds_read_b128 v[200:203], v150 offset:17408
	ds_read_b128 v[204:207], v150 offset:18432
	ds_read_b128 v[208:211], v150 offset:19456
	ds_read_b128 v[212:215], v150 offset:20480
	ds_read_b128 v[216:219], v150 offset:21504
	ds_read_b128 v[220:223], v150 offset:22528
	ds_read_b128 v[224:227], v150 offset:23552
	global_load_lds_dwordx4 v[146:147], off
	s_add_i32 m0, s20, 0x2000
	s_add_u32 s20, s26, 0xc0000
	v_lshl_add_u64 v[176:177], s[26:27], 0, v[134:135]
	s_addc_u32 s21, s27, 0
	s_add_i32 s64, s65, s28
	global_load_lds_dwordx4 v[176:177], off
	v_lshl_add_u64 v[228:229], s[20:21], 0, v[136:137]
	s_mov_b32 m0, s64
	v_lshl_add_u64 v[230:231], s[58:59], 0, v[134:135]
	global_load_lds_dwordx4 v[228:229], off
	v_lshl_add_u64 v[228:229], s[20:21], 0, v[134:135]
	s_add_i32 m0, s64, 0x2000
	s_nop 0
	global_load_lds_dwordx4 v[228:229], off
	v_lshl_add_u64 v[228:229], s[58:59], 0, v[136:137]
	s_mov_b32 m0, s37
	s_nop 0
	global_load_lds_dwordx4 v[228:229], off
	s_mov_b32 m0, s40
	s_nop 0
	global_load_lds_dwordx4 v[230:231], off
	s_waitcnt vmcnt(8)
	s_waitcnt lgkmcnt(0)
	s_setprio 1
	s_barrier
; #define PG8_STAGE(bufoff, gbase, voff) do { _Pragma("unroll") for (int _i = 0; _i < 2; ++_i) \
;         __builtin_amdgcn_global_load_lds((const unsigned*)((const char*)(gbase) + (voff)[_i]), (PG8_LAS unsigned*)(lds + (bufoff) + ldsw + _i * 8192), 16, 0, 0); } while (0)
; #define PG8_LDA(dst, b, h) do { _Pragma("unroll") for (int m = 0; m < 4; ++m) _Pragma("unroll") for (int k = 0; k < 2; ++k) dst[m][k] = *(const PG8_LAS bf16x8*)(lds + PG8_SA(b, h) + aoff + m * 2048 + k * 1024); } while (0)
; #define PG8_LDB(dst, b, h) do { _Pragma("unroll") for (int n = 0; n < 2; ++n) _Pragma("unroll") for (int k = 0; k < 2; ++k) dst[n][k] = *(const PG8_LAS bf16x8*)(lds + PG8_SB(b, h) + boff + n * 2048 + k * 1024); } while (0)
; #define PG8_MMA(ai, bj, At, Bt) do { __builtin_amdgcn_s_setprio(1); _Pragma("unroll") for (int m = 0; m < 4; ++m) _Pragma("unroll") for (int n = 0; n < 2; ++n) _Pragma("unroll") for (int k = 0; k < 2; ++k) \
;         acc[ai][bj][m][n] = __builtin_amdgcn_mfma_f32_16x16x32_bf16(Bt[n][k], At[m][k], acc[ai][bj][m][n], 0, 0, 0); __builtin_amdgcn_s_setprio(0); } while (0)
; #define PG8_WAIT_V(n) asm volatile("s_waitcnt vmcnt(" #n ")" ::: "memory")
; #define PG8_WAIT_L(n) asm volatile("s_waitcnt lgkmcnt(" #n ")" ::: "memory")
; #define PG8_BAR __builtin_amdgcn_s_barrier()
; #define PG8_SCHED __builtin_amdgcn_sched_barrier(0)
; template <class Epi, class Sched, bool ALIGN_EPI = false, bool SP2 = false>
; __device__ __forceinline__ void gemm_phase(PG8_LAS unsigned char* lds, const Gemm g, const Sched& S, const Epi& E) {
;     ...
;             PG8_WAIT_V(8); PG8_WAIT_L(0); PG8_BAR; PG8_MMA(1, 0, At, B0); PG8_MMA(1, 1, At, B1); PG8_BAR; PG8_SCHED;
;             PG8_LDB(B0, 1, 0); PG8_LDB(B1, 1, 1); PG8_SCHED; PG8_LDA(At, 1, 0); PG8_STAGE(PG8_SA(0, 1), a2 + hstep, voffA);
;             PG8_WAIT_V(8); PG8_WAIT_L(0); PG8_BAR; PG8_MMA(0, 0, At, B0); PG8_MMA(0, 1, At, B1); PG8_BAR; PG8_SCHED;
	v_mfma_f32_16x16x32_bf16 v[62:65], v[142:145], v[184:187], v[62:65]
	v_mfma_f32_16x16x32_bf16 v[58:61], v[156:159], v[184:187], v[58:61]
	v_mfma_f32_16x16x32_bf16 v[50:53], v[142:145], v[204:207], v[50:53]
	v_mfma_f32_16x16x32_bf16 v[42:45], v[156:159], v[204:207], v[42:45]
	v_mfma_f32_16x16x32_bf16 v[34:37], v[142:145], v[212:215], v[34:37]
	v_mfma_f32_16x16x32_bf16 v[26:29], v[156:159], v[212:215], v[26:29]
	v_mfma_f32_16x16x32_bf16 v[18:21], v[142:145], v[220:223], v[18:21]
	v_mfma_f32_16x16x32_bf16 v[10:13], v[156:159], v[220:223], v[10:13]
	v_mfma_f32_16x16x32_bf16 v[62:65], v[152:155], v[200:203], v[62:65]
	v_mfma_f32_16x16x32_bf16 v[58:61], v[160:163], v[200:203], v[58:61]
	v_mfma_f32_16x16x32_bf16 v[50:53], v[152:155], v[208:211], v[50:53]
	v_mfma_f32_16x16x32_bf16 v[42:45], v[160:163], v[208:211], v[42:45]
	v_mfma_f32_16x16x32_bf16 v[34:37], v[152:155], v[216:219], v[34:37]
	v_mfma_f32_16x16x32_bf16 v[26:29], v[160:163], v[216:219], v[26:29]
	v_mfma_f32_16x16x32_bf16 v[18:21], v[152:155], v[224:227], v[18:21]
	v_mfma_f32_16x16x32_bf16 v[10:13], v[160:163], v[224:227], v[10:13]
	v_mfma_f32_16x16x32_bf16 v[54:57], v[164:167], v[184:187], v[54:57]
	v_mfma_f32_16x16x32_bf16 v[46:49], v[172:175], v[184:187], v[46:49]
	v_mfma_f32_16x16x32_bf16 v[38:41], v[164:167], v[204:207], v[38:41]
	v_mfma_f32_16x16x32_bf16 v[30:33], v[172:175], v[204:207], v[30:33]
	v_mfma_f32_16x16x32_bf16 v[22:25], v[164:167], v[212:215], v[22:25]
	v_mfma_f32_16x16x32_bf16 v[14:17], v[172:175], v[212:215], v[14:17]
	v_mfma_f32_16x16x32_bf16 v[6:9], v[164:167], v[220:223], v[6:9]
	v_mfma_f32_16x16x32_bf16 v[2:5], v[172:175], v[220:223], v[2:5]
	v_mfma_f32_16x16x32_bf16 v[54:57], v[168:171], v[200:203], v[54:57]
	v_mfma_f32_16x16x32_bf16 v[46:49], v[180:183], v[200:203], v[46:49]
	v_mfma_f32_16x16x32_bf16 v[38:41], v[168:171], v[208:211], v[38:41]
	v_mfma_f32_16x16x32_bf16 v[30:33], v[180:183], v[208:211], v[30:33]
	v_mfma_f32_16x16x32_bf16 v[22:25], v[168:171], v[216:219], v[22:25]
	v_mfma_f32_16x16x32_bf16 v[14:17], v[180:183], v[216:219], v[14:17]
	v_mfma_f32_16x16x32_bf16 v[6:9], v[168:171], v[224:227], v[6:9]
	v_mfma_f32_16x16x32_bf16 v[2:5], v[180:183], v[224:227], v[2:5]
	s_barrier
	s_setprio 0
	s_add_i32 s64, 0, 0x18000
	v_add_u32_e32 v151, s64, v148
	s_add_i32 s65, 0, 0x1c000
	ds_read_b128 v[142:145], v151
	ds_read_b128 v[152:155], v151 offset:1024
	ds_read_b128 v[156:159], v151 offset:2048
	ds_read_b128 v[160:163], v151 offset:3072
	v_add_u32_e32 v151, s65, v148
	ds_read_b128 v[164:167], v151
	ds_read_b128 v[168:171], v151 offset:1024
	ds_read_b128 v[172:175], v151 offset:2048
	ds_read_b128 v[180:183], v151 offset:3072
	s_add_u32 s20, s58, 0xc0000
	s_addc_u32 s21, s59, 0
	s_mov_b32 m0, s41
	v_lshl_add_u64 v[232:233], s[20:21], 0, v[136:137]
	ds_read_b128 v[184:187], v150 offset:32768
	ds_read_b128 v[200:203], v150 offset:33792
	ds_read_b128 v[204:207], v150 offset:34816
	ds_read_b128 v[208:211], v150 offset:35840
	ds_read_b128 v[212:215], v150 offset:36864
	ds_read_b128 v[216:219], v150 offset:37888
	ds_read_b128 v[220:223], v150 offset:38912
	ds_read_b128 v[224:227], v150 offset:39936
	global_load_lds_dwordx4 v[232:233], off
	v_lshl_add_u64 v[232:233], s[20:21], 0, v[134:135]
	s_mov_b32 m0, s42
	s_nop 0
	global_load_lds_dwordx4 v[232:233], off
	s_waitcnt vmcnt(8)
	s_waitcnt lgkmcnt(0)
	s_setprio 1
	s_barrier
	v_mfma_f32_16x16x32_bf16 v[130:133], v[142:145], v[184:187], v[130:133]
	v_mfma_f32_16x16x32_bf16 v[126:129], v[156:159], v[184:187], v[126:129]
	v_mfma_f32_16x16x32_bf16 v[118:121], v[142:145], v[204:207], v[118:121]
	v_mfma_f32_16x16x32_bf16 v[110:113], v[156:159], v[204:207], v[110:113]
	v_mfma_f32_16x16x32_bf16 v[102:105], v[142:145], v[212:215], v[102:105]
	v_mfma_f32_16x16x32_bf16 v[94:97], v[156:159], v[212:215], v[94:97]
	v_mfma_f32_16x16x32_bf16 v[86:89], v[142:145], v[220:223], v[86:89]
	v_mfma_f32_16x16x32_bf16 v[74:77], v[156:159], v[220:223], v[74:77]
	v_mfma_f32_16x16x32_bf16 v[130:133], v[152:155], v[200:203], v[130:133]
	v_mfma_f32_16x16x32_bf16 v[126:129], v[160:163], v[200:203], v[126:129]
	v_mfma_f32_16x16x32_bf16 v[118:121], v[152:155], v[208:211], v[118:121]
	v_mfma_f32_16x16x32_bf16 v[110:113], v[160:163], v[208:211], v[110:113]
	v_mfma_f32_16x16x32_bf16 v[102:105], v[152:155], v[216:219], v[102:105]
	v_mfma_f32_16x16x32_bf16 v[94:97], v[160:163], v[216:219], v[94:97]
	v_mfma_f32_16x16x32_bf16 v[86:89], v[152:155], v[224:227], v[86:89]
	v_mfma_f32_16x16x32_bf16 v[74:77], v[160:163], v[224:227], v[74:77]
	v_mfma_f32_16x16x32_bf16 v[122:125], v[164:167], v[184:187], v[122:125]
	v_mfma_f32_16x16x32_bf16 v[114:117], v[172:175], v[184:187], v[114:117]
	v_mfma_f32_16x16x32_bf16 v[106:109], v[164:167], v[204:207], v[106:109]
	v_mfma_f32_16x16x32_bf16 v[98:101], v[172:175], v[204:207], v[98:101]
	v_mfma_f32_16x16x32_bf16 v[90:93], v[164:167], v[212:215], v[90:93]
	v_mfma_f32_16x16x32_bf16 v[78:81], v[172:175], v[212:215], v[78:81]
	v_mfma_f32_16x16x32_bf16 v[70:73], v[164:167], v[220:223], v[70:73]
	v_mfma_f32_16x16x32_bf16 v[66:69], v[172:175], v[220:223], v[66:69]
	v_mfma_f32_16x16x32_bf16 v[122:125], v[168:171], v[200:203], v[122:125]
	v_mfma_f32_16x16x32_bf16 v[114:117], v[180:183], v[200:203], v[114:117]
	v_mfma_f32_16x16x32_bf16 v[106:109], v[168:171], v[208:211], v[106:109]
	v_mfma_f32_16x16x32_bf16 v[98:101], v[180:183], v[208:211], v[98:101]
	v_mfma_f32_16x16x32_bf16 v[90:93], v[168:171], v[216:219], v[90:93]
	v_mfma_f32_16x16x32_bf16 v[78:81], v[180:183], v[216:219], v[78:81]
	v_mfma_f32_16x16x32_bf16 v[70:73], v[168:171], v[224:227], v[70:73]
	v_mfma_f32_16x16x32_bf16 v[66:69], v[180:183], v[224:227], v[66:69]
	s_barrier
; #define PG8_STAGE(bufoff, gbase, voff) do { _Pragma("unroll") for (int _i = 0; _i < 2; ++_i) \
;         __builtin_amdgcn_global_load_lds((const unsigned*)((const char*)(gbase) + (voff)[_i]), (PG8_LAS unsigned*)(lds + (bufoff) + ldsw + _i * 8192), 16, 0, 0); } while (0)
; #define PG8_LDA(dst, b, h) do { _Pragma("unroll") for (int m = 0; m < 4; ++m) _Pragma("unroll") for (int k = 0; k < 2; ++k) dst[m][k] = *(const PG8_LAS bf16x8*)(lds + PG8_SA(b, h) + aoff + m * 2048 + k * 1024); } while (0)
; #define PG8_MMA(ai, bj, At, Bt) do { __builtin_amdgcn_s_setprio(1); _Pragma("unroll") for (int m = 0; m < 4; ++m) _Pragma("unroll") for (int n = 0; n < 2; ++n) _Pragma("unroll") for (int k = 0; k < 2; ++k) \
;         acc[ai][bj][m][n] = __builtin_amdgcn_mfma_f32_16x16x32_bf16(Bt[n][k], At[m][k], acc[ai][bj][m][n], 0, 0, 0); __builtin_amdgcn_s_setprio(0); } while (0)
; #define PG8_WAIT_V(n) asm volatile("s_waitcnt vmcnt(" #n ")" ::: "memory")
; #define PG8_WAIT_L(n) asm volatile("s_waitcnt lgkmcnt(" #n ")" ::: "memory")
; #define PG8_BAR __builtin_amdgcn_s_barrier()
; #define PG8_SCHED __builtin_amdgcn_sched_barrier(0)
; template <class Epi, class Sched, bool ALIGN_EPI = false, bool SP2 = false>
; __device__ __forceinline__ void gemm_phase(PG8_LAS unsigned char* lds, const Gemm g, const Sched& S, const Epi& E) {
;     ...
;             PG8_LDA(At, 1, 1); PG8_STAGE(PG8_SB(1, 0), b3, voffB); PG8_STAGE(PG8_SB(1, 1), b3 + hstep, voffB); PG8_STAGE(PG8_SA(1, 0), a3, voffA);
;             PG8_WAIT_V(8); PG8_WAIT_L(0); PG8_BAR; PG8_MMA(1, 0, At, B0); PG8_MMA(1, 1, At, B1); PG8_BAR; PG8_SCHED;
;     ...
;         if constexpr (ALIGN_EPI) { if (wr == 0) PG8_BAR; }
	s_setprio 0
	s_add_i32 s20, s64, s28
	v_lshl_add_u64 v[146:147], v[146:147], 0, s[38:39]
	s_mov_b32 m0, s20
	ds_read_b128 v[184:187], v150 offset:49152
	ds_read_b128 v[200:203], v150 offset:50176
	ds_read_b128 v[204:207], v150 offset:51200
	ds_read_b128 v[208:211], v150 offset:52224
	ds_read_b128 v[212:215], v150 offset:53248
	ds_read_b128 v[216:219], v150 offset:54272
	ds_read_b128 v[220:223], v150 offset:55296
	ds_read_b128 v[224:227], v150 offset:56320
	global_load_lds_dwordx4 v[146:147], off
	s_add_i32 m0, s20, 0x2000
	s_add_u32 s20, s26, 0xc0080
	v_lshl_add_u64 v[146:147], v[176:177], 0, s[38:39]
	s_addc_u32 s21, s27, 0
	s_add_i32 s26, s65, s28
	global_load_lds_dwordx4 v[146:147], off
	v_lshl_add_u64 v[146:147], s[20:21], 0, v[136:137]
	s_mov_b32 m0, s26
	s_nop 0
	global_load_lds_dwordx4 v[146:147], off
	v_lshl_add_u64 v[146:147], s[20:21], 0, v[134:135]
	s_add_i32 m0, s26, 0x2000
	s_nop 0
	global_load_lds_dwordx4 v[146:147], off
	v_lshl_add_u64 v[146:147], v[228:229], 0, s[38:39]
	s_mov_b32 m0, s49
	s_nop 0
	global_load_lds_dwordx4 v[146:147], off
	v_lshl_add_u64 v[146:147], v[230:231], 0, s[38:39]
	s_mov_b32 m0, s52
	s_nop 0
	global_load_lds_dwordx4 v[146:147], off
	s_waitcnt vmcnt(8)
	s_waitcnt lgkmcnt(0)
	s_setprio 1
	s_barrier
	v_mfma_f32_16x16x32_bf16 v[62:65], v[142:145], v[184:187], v[62:65]
	v_mfma_f32_16x16x32_bf16 v[58:61], v[156:159], v[184:187], v[58:61]
	v_mfma_f32_16x16x32_bf16 v[50:53], v[142:145], v[204:207], v[50:53]
	v_mfma_f32_16x16x32_bf16 v[42:45], v[156:159], v[204:207], v[42:45]
	v_mfma_f32_16x16x32_bf16 v[34:37], v[142:145], v[212:215], v[34:37]
	v_mfma_f32_16x16x32_bf16 v[26:29], v[156:159], v[212:215], v[26:29]
	v_mfma_f32_16x16x32_bf16 v[18:21], v[142:145], v[220:223], v[18:21]
	v_mfma_f32_16x16x32_bf16 v[10:13], v[156:159], v[220:223], v[10:13]
	v_mfma_f32_16x16x32_bf16 v[62:65], v[152:155], v[200:203], v[62:65]
	v_mfma_f32_16x16x32_bf16 v[58:61], v[160:163], v[200:203], v[58:61]
	v_mfma_f32_16x16x32_bf16 v[50:53], v[152:155], v[208:211], v[50:53]
	v_mfma_f32_16x16x32_bf16 v[42:45], v[160:163], v[208:211], v[42:45]
	v_mfma_f32_16x16x32_bf16 v[34:37], v[152:155], v[216:219], v[34:37]
	v_mfma_f32_16x16x32_bf16 v[26:29], v[160:163], v[216:219], v[26:29]
	v_mfma_f32_16x16x32_bf16 v[18:21], v[152:155], v[224:227], v[18:21]
	v_mfma_f32_16x16x32_bf16 v[10:13], v[160:163], v[224:227], v[10:13]
	v_mfma_f32_16x16x32_bf16 v[54:57], v[164:167], v[184:187], v[54:57]
	v_mfma_f32_16x16x32_bf16 v[46:49], v[172:175], v[184:187], v[46:49]
	v_mfma_f32_16x16x32_bf16 v[38:41], v[164:167], v[204:207], v[38:41]
	v_mfma_f32_16x16x32_bf16 v[30:33], v[172:175], v[204:207], v[30:33]
	v_mfma_f32_16x16x32_bf16 v[22:25], v[164:167], v[212:215], v[22:25]
	v_mfma_f32_16x16x32_bf16 v[14:17], v[172:175], v[212:215], v[14:17]
	v_mfma_f32_16x16x32_bf16 v[6:9], v[164:167], v[220:223], v[6:9]
	v_mfma_f32_16x16x32_bf16 v[2:5], v[172:175], v[220:223], v[2:5]
	v_mfma_f32_16x16x32_bf16 v[54:57], v[168:171], v[200:203], v[54:57]
	v_mfma_f32_16x16x32_bf16 v[46:49], v[180:183], v[200:203], v[46:49]
	v_mfma_f32_16x16x32_bf16 v[38:41], v[168:171], v[208:211], v[38:41]
	v_mfma_f32_16x16x32_bf16 v[30:33], v[180:183], v[208:211], v[30:33]
	v_mfma_f32_16x16x32_bf16 v[22:25], v[168:171], v[216:219], v[22:25]
	v_mfma_f32_16x16x32_bf16 v[14:17], v[180:183], v[216:219], v[14:17]
	v_mfma_f32_16x16x32_bf16 v[6:9], v[168:171], v[224:227], v[6:9]
	v_mfma_f32_16x16x32_bf16 v[2:5], v[180:183], v[224:227], v[2:5]
	s_barrier
	s_setprio 0
	s_add_i32 s63, s63, 2
	s_add_u32 s61, s61, 0x100
	s_addc_u32 s62, s62, 0
	s_cmp_gt_u32 s63, 45
	s_mov_b64 s[20:21], s[24:25]
	s_cbranch_scc0 .LBB0_1035
	s_and_b64 vcc, exec, s[16:17]
	s_cbranch_vccz .LBB0_1038
	s_barrier
